# all GEMM K-loops: LDS-DMA loads use scalar-base + 32-bit lane offset addressing where the 64-bit vector address was a pure temporary
# speedup vs baseline: 1.0103x; 1.0031x over previous
; #define PG8_STAGE(bufoff, gbase, voff) do { _Pragma("unroll") for (int _i = 0; _i < 2; ++_i) \
;         __builtin_amdgcn_global_load_lds((const unsigned*)((const char*)(gbase) + (voff)[_i]), (PG8_LAS unsigned*)(lds + (bufoff) + ldsw + _i * 8192), 16, 0, 0); } while (0)
; #define PG8_LDA(dst, b, h) do { _Pragma("unroll") for (int m = 0; m < 4; ++m) _Pragma("unroll") for (int k = 0; k < 2; ++k) dst[m][k] = *(const PG8_LAS bf16x8*)(lds + PG8_SA(b, h) + aoff + m * 2048 + k * 1024); } while (0)
; #define PG8_LDB(dst, b, h) do { _Pragma("unroll") for (int n = 0; n < 2; ++n) _Pragma("unroll") for (int k = 0; k < 2; ++k) dst[n][k] = *(const PG8_LAS bf16x8*)(lds + PG8_SB(b, h) + boff + n * 2048 + k * 1024); } while (0)
; #define PG8_MMA(ai, bj, At, Bt) do { __builtin_amdgcn_s_setprio(1); _Pragma("unroll") for (int m = 0; m < 4; ++m) _Pragma("unroll") for (int n = 0; n < 2; ++n) _Pragma("unroll") for (int k = 0; k < 2; ++k) \
;         acc[ai][bj][m][n] = __builtin_amdgcn_mfma_f32_16x16x32_bf16(Bt[n][k], At[m][k], acc[ai][bj][m][n], 0, 0, 0); __builtin_amdgcn_s_setprio(0); } while (0)
; #define PG8_WAIT_V(n) asm volatile("s_waitcnt vmcnt(" #n ")" ::: "memory")
; #define PG8_WAIT_L(n) asm volatile("s_waitcnt lgkmcnt(" #n ")" ::: "memory")
; #define PG8_BAR __builtin_amdgcn_s_barrier()
; #define PG8_SCHED __builtin_amdgcn_sched_barrier(0)
; template <class Epi, class Sched, bool ALIGN_EPI = false, bool SP2 = false>
; __device__ __forceinline__ void gemm_phase(PG8_LAS unsigned char* lds, const Gemm g, const Sched& S, const Epi& E) {
;     ...
;             PG8_LDB(B0, 0, 0); PG8_LDB(B1, 0, 1); PG8_SCHED; PG8_LDA(At, 0, 0); PG8_STAGE(PG8_SA(1, 1), a1 + hstep, voffA);
;             PG8_WAIT_V(8); PG8_WAIT_L(0); PG8_BAR; PG8_MMA(0, 0, At, B0); PG8_MMA(0, 1, At, B1); PG8_BAR; PG8_SCHED;
;             PG8_LDA(At, 0, 1); PG8_STAGE(PG8_SB(0, 0), b2, voffB); PG8_STAGE(PG8_SB(0, 1), b2 + hstep, voffB); PG8_STAGE(PG8_SA(0, 0), a2, voffA);
;             PG8_WAIT_V(8); PG8_WAIT_L(0); PG8_BAR; PG8_MMA(1, 0, At, B0); PG8_MMA(1, 1, At, B1); PG8_BAR; PG8_SCHED;
.LBB0_307:
	s_add_u32 s4, s42, s0
	s_addc_u32 s5, s43, s1
	s_add_u32 s4, s4, 0x2cc00100
	s_addc_u32 s5, s5, 0
	s_add_u32 s20, s48, s0
	s_addc_u32 s21, s67, s1
	s_add_i32 s22, 0, 0x10000
	s_cmpk_eq_i32 s0, 0xf00
	s_cselect_b32 s7, s55, s5
	s_cselect_b32 s6, s54, s4
	s_cselect_b32 s5, s53, s21
	s_cselect_b32 s4, s52, s20
	s_add_i32 s23, 0, 0x14000
	v_add_u32_e32 v172, s22, v158
	v_add_u32_e32 v188, s23, v158
	ds_read_b128 v[160:163], v172
	ds_read_b128 v[164:167], v172 offset:1024
	ds_read_b128 v[168:171], v172 offset:2048
	ds_read_b128 v[172:175], v172 offset:3072
	ds_read_b128 v[176:179], v188
	ds_read_b128 v[180:183], v188 offset:1024
	ds_read_b128 v[184:187], v188 offset:2048
	ds_read_b128 v[188:191], v188 offset:3072
	v_lshl_add_u64 v[228:229], v[152:153], 0, s[0:1]
	s_add_i32 m0, s12, 0xc000
	ds_read_b128 v[192:195], v159
	ds_read_b128 v[196:199], v159 offset:1024
	ds_read_b128 v[200:203], v159 offset:2048
	ds_read_b128 v[204:207], v159 offset:3072
	ds_read_b128 v[208:211], v159 offset:4096
	ds_read_b128 v[212:215], v159 offset:5120
	ds_read_b128 v[216:219], v159 offset:6144
	ds_read_b128 v[224:227], v159 offset:7168
	global_load_lds_dwordx4 v[228:229], off
	s_add_i32 m0, s12, 0xe000
	v_lshl_add_u64 v[228:229], v[154:155], 0, s[0:1]
	global_load_lds_dwordx4 v[228:229], off
	s_waitcnt vmcnt(8) lgkmcnt(0)
	s_barrier
	v_mfma_f32_16x16x32_bf16 v[144:147], v[160:163], v[192:195], v[144:147]
	v_mfma_f32_16x16x32_bf16 v[122:125], v[168:171], v[192:195], v[122:125]
	v_mfma_f32_16x16x32_bf16 v[118:121], v[160:163], v[200:203], v[118:121]
	v_mfma_f32_16x16x32_bf16 v[114:117], v[168:171], v[200:203], v[114:117]
	v_mfma_f32_16x16x32_bf16 v[102:105], v[160:163], v[208:211], v[102:105]
	v_mfma_f32_16x16x32_bf16 v[98:101], v[168:171], v[208:211], v[98:101]
	v_mfma_f32_16x16x32_bf16 v[86:89], v[160:163], v[216:219], v[86:89]
	v_mfma_f32_16x16x32_bf16 v[82:85], v[168:171], v[216:219], v[82:85]
	v_mfma_f32_16x16x32_bf16 v[144:147], v[164:167], v[196:199], v[144:147]
	v_mfma_f32_16x16x32_bf16 v[122:125], v[172:175], v[196:199], v[122:125]
	v_mfma_f32_16x16x32_bf16 v[118:121], v[164:167], v[204:207], v[118:121]
	v_mfma_f32_16x16x32_bf16 v[114:117], v[172:175], v[204:207], v[114:117]
	v_mfma_f32_16x16x32_bf16 v[102:105], v[164:167], v[212:215], v[102:105]
	v_mfma_f32_16x16x32_bf16 v[98:101], v[172:175], v[212:215], v[98:101]
	v_mfma_f32_16x16x32_bf16 v[86:89], v[164:167], v[224:227], v[86:89]
	v_mfma_f32_16x16x32_bf16 v[82:85], v[172:175], v[224:227], v[82:85]
	v_mfma_f32_16x16x32_bf16 v[110:113], v[176:179], v[192:195], v[110:113]
	v_mfma_f32_16x16x32_bf16 v[106:109], v[184:187], v[192:195], v[106:109]
	v_mfma_f32_16x16x32_bf16 v[94:97], v[176:179], v[200:203], v[94:97]
	v_mfma_f32_16x16x32_bf16 v[90:93], v[184:187], v[200:203], v[90:93]
	v_mfma_f32_16x16x32_bf16 v[78:81], v[176:179], v[208:211], v[78:81]
	v_mfma_f32_16x16x32_bf16 v[74:77], v[184:187], v[208:211], v[74:77]
	v_mfma_f32_16x16x32_bf16 v[70:73], v[176:179], v[216:219], v[70:73]
	v_mfma_f32_16x16x32_bf16 v[66:69], v[184:187], v[216:219], v[66:69]
	v_mfma_f32_16x16x32_bf16 v[110:113], v[180:183], v[196:199], v[110:113]
	v_mfma_f32_16x16x32_bf16 v[106:109], v[188:191], v[196:199], v[106:109]
	v_mfma_f32_16x16x32_bf16 v[94:97], v[180:183], v[204:207], v[94:97]
	v_mfma_f32_16x16x32_bf16 v[90:93], v[188:191], v[204:207], v[90:93]
	v_mfma_f32_16x16x32_bf16 v[78:81], v[180:183], v[212:215], v[78:81]
	v_mfma_f32_16x16x32_bf16 v[74:77], v[188:191], v[212:215], v[74:77]
	v_mfma_f32_16x16x32_bf16 v[70:73], v[180:183], v[224:227], v[70:73]
	v_mfma_f32_16x16x32_bf16 v[66:69], v[188:191], v[224:227], v[66:69]
	s_barrier
	s_add_i32 s20, s22, s9
	v_lshl_add_u64 v[228:229], s[4:5], 0, v[0:1]
	s_mov_b32 m0, s20
	ds_read_b128 v[192:195], v159 offset:16384
	ds_read_b128 v[196:199], v159 offset:17408
	ds_read_b128 v[200:203], v159 offset:18432
	ds_read_b128 v[204:207], v159 offset:19456
	ds_read_b128 v[208:211], v159 offset:20480
	ds_read_b128 v[212:215], v159 offset:21504
	ds_read_b128 v[216:219], v159 offset:22528
	ds_read_b128 v[224:227], v159 offset:23552
	global_load_lds_dwordx4 v[228:229], off
	s_add_i32 m0, s20, 0x2000
	s_add_u32 s20, s4, 0x80000
	v_lshl_add_u64 v[230:231], s[4:5], 0, v[126:127]
	s_addc_u32 s21, s5, 0
	s_add_i32 s22, s23, s9
	global_load_lds_dwordx4 v[230:231], off
	s_mov_b32 m0, s22
	v_lshl_add_u64 v[244:245], s[6:7], 0, v[148:149]
	global_load_lds_dwordx4 v0, s[20:21]
	s_add_i32 m0, s22, 0x2000
	s_nop 0
	global_load_lds_dwordx4 v126, s[20:21]
	s_mov_b32 m0, s12
	v_lshl_add_u64 v[232:233], s[6:7], 0, v[150:151]
	global_load_lds_dwordx4 v[232:233], off
	s_mov_b32 m0, s13
	s_nop 0
	global_load_lds_dwordx4 v[244:245], off
	s_waitcnt vmcnt(8) lgkmcnt(0)
	s_barrier
; #define PG8_STAGE(bufoff, gbase, voff) do { _Pragma("unroll") for (int _i = 0; _i < 2; ++_i) \
;         __builtin_amdgcn_global_load_lds((const unsigned*)((const char*)(gbase) + (voff)[_i]), (PG8_LAS unsigned*)(lds + (bufoff) + ldsw + _i * 8192), 16, 0, 0); } while (0)
; #define PG8_LDA(dst, b, h) do { _Pragma("unroll") for (int m = 0; m < 4; ++m) _Pragma("unroll") for (int k = 0; k < 2; ++k) dst[m][k] = *(const PG8_LAS bf16x8*)(lds + PG8_SA(b, h) + aoff + m * 2048 + k * 1024); } while (0)
; #define PG8_LDB(dst, b, h) do { _Pragma("unroll") for (int n = 0; n < 2; ++n) _Pragma("unroll") for (int k = 0; k < 2; ++k) dst[n][k] = *(const PG8_LAS bf16x8*)(lds + PG8_SB(b, h) + boff + n * 2048 + k * 1024); } while (0)
; #define PG8_MMA(ai, bj, At, Bt) do { __builtin_amdgcn_s_setprio(1); _Pragma("unroll") for (int m = 0; m < 4; ++m) _Pragma("unroll") for (int n = 0; n < 2; ++n) _Pragma("unroll") for (int k = 0; k < 2; ++k) \
;         acc[ai][bj][m][n] = __builtin_amdgcn_mfma_f32_16x16x32_bf16(Bt[n][k], At[m][k], acc[ai][bj][m][n], 0, 0, 0); __builtin_amdgcn_s_setprio(0); } while (0)
; #define PG8_WAIT_V(n) asm volatile("s_waitcnt vmcnt(" #n ")" ::: "memory")
; #define PG8_WAIT_L(n) asm volatile("s_waitcnt lgkmcnt(" #n ")" ::: "memory")
; #define PG8_BAR __builtin_amdgcn_s_barrier()
; #define PG8_SCHED __builtin_amdgcn_sched_barrier(0)
; template <class Epi, class Sched, bool ALIGN_EPI = false, bool SP2 = false>
; __device__ __forceinline__ void gemm_phase(PG8_LAS unsigned char* lds, const Gemm g, const Sched& S, const Epi& E) {
;     ...
;             PG8_WAIT_V(8); PG8_WAIT_L(0); PG8_BAR; PG8_MMA(1, 0, At, B0); PG8_MMA(1, 1, At, B1); PG8_BAR; PG8_SCHED;
;             PG8_LDB(B0, 1, 0); PG8_LDB(B1, 1, 1); PG8_SCHED; PG8_LDA(At, 1, 0); PG8_STAGE(PG8_SA(0, 1), a2 + hstep, voffA);
;             PG8_WAIT_V(8); PG8_WAIT_L(0); PG8_BAR; PG8_MMA(0, 0, At, B0); PG8_MMA(0, 1, At, B1); PG8_BAR; PG8_SCHED;
	v_mfma_f32_16x16x32_bf16 v[62:65], v[160:163], v[192:195], v[62:65]
	v_mfma_f32_16x16x32_bf16 v[58:61], v[168:171], v[192:195], v[58:61]
	v_mfma_f32_16x16x32_bf16 v[54:57], v[160:163], v[200:203], v[54:57]
	v_mfma_f32_16x16x32_bf16 v[50:53], v[168:171], v[200:203], v[50:53]
	v_mfma_f32_16x16x32_bf16 v[38:41], v[160:163], v[208:211], v[38:41]
	v_mfma_f32_16x16x32_bf16 v[34:37], v[168:171], v[208:211], v[34:37]
	v_mfma_f32_16x16x32_bf16 v[22:25], v[160:163], v[216:219], v[22:25]
	v_mfma_f32_16x16x32_bf16 v[18:21], v[168:171], v[216:219], v[18:21]
	v_mfma_f32_16x16x32_bf16 v[62:65], v[164:167], v[196:199], v[62:65]
	v_mfma_f32_16x16x32_bf16 v[58:61], v[172:175], v[196:199], v[58:61]
	v_mfma_f32_16x16x32_bf16 v[54:57], v[164:167], v[204:207], v[54:57]
	v_mfma_f32_16x16x32_bf16 v[50:53], v[172:175], v[204:207], v[50:53]
	v_mfma_f32_16x16x32_bf16 v[38:41], v[164:167], v[212:215], v[38:41]
	v_mfma_f32_16x16x32_bf16 v[34:37], v[172:175], v[212:215], v[34:37]
	v_mfma_f32_16x16x32_bf16 v[22:25], v[164:167], v[224:227], v[22:25]
	v_mfma_f32_16x16x32_bf16 v[18:21], v[172:175], v[224:227], v[18:21]
	v_mfma_f32_16x16x32_bf16 v[46:49], v[176:179], v[192:195], v[46:49]
	v_mfma_f32_16x16x32_bf16 v[42:45], v[184:187], v[192:195], v[42:45]
	v_mfma_f32_16x16x32_bf16 v[30:33], v[176:179], v[200:203], v[30:33]
	v_mfma_f32_16x16x32_bf16 v[26:29], v[184:187], v[200:203], v[26:29]
	v_mfma_f32_16x16x32_bf16 v[14:17], v[176:179], v[208:211], v[14:17]
	v_mfma_f32_16x16x32_bf16 v[10:13], v[184:187], v[208:211], v[10:13]
	v_mfma_f32_16x16x32_bf16 v[6:9], v[176:179], v[216:219], v[6:9]
	v_mfma_f32_16x16x32_bf16 v[2:5], v[184:187], v[216:219], v[2:5]
	v_mfma_f32_16x16x32_bf16 v[46:49], v[180:183], v[196:199], v[46:49]
	v_mfma_f32_16x16x32_bf16 v[42:45], v[188:191], v[196:199], v[42:45]
	v_mfma_f32_16x16x32_bf16 v[30:33], v[180:183], v[204:207], v[30:33]
	v_mfma_f32_16x16x32_bf16 v[26:29], v[188:191], v[204:207], v[26:29]
	v_mfma_f32_16x16x32_bf16 v[14:17], v[180:183], v[212:215], v[14:17]
	v_mfma_f32_16x16x32_bf16 v[10:13], v[188:191], v[212:215], v[10:13]
	v_mfma_f32_16x16x32_bf16 v[6:9], v[180:183], v[224:227], v[6:9]
	v_mfma_f32_16x16x32_bf16 v[2:5], v[188:191], v[224:227], v[2:5]
	s_barrier
	s_add_i32 s20, 0, 0x18000
	s_add_i32 s21, 0, 0x1c000
	v_add_u32_e32 v172, s20, v158
	v_add_u32_e32 v188, s21, v158
	ds_read_b128 v[160:163], v172
	ds_read_b128 v[164:167], v172 offset:1024
	ds_read_b128 v[168:171], v172 offset:2048
	ds_read_b128 v[172:175], v172 offset:3072
	ds_read_b128 v[176:179], v188
	ds_read_b128 v[180:183], v188 offset:1024
	ds_read_b128 v[184:187], v188 offset:2048
	ds_read_b128 v[188:191], v188 offset:3072
	s_add_u32 s6, s6, 0x80000
	s_addc_u32 s7, s7, 0
	s_mov_b32 m0, s14
	ds_read_b128 v[192:195], v159 offset:32768
	ds_read_b128 v[196:199], v159 offset:33792
	ds_read_b128 v[200:203], v159 offset:34816
	ds_read_b128 v[204:207], v159 offset:35840
	ds_read_b128 v[208:211], v159 offset:36864
	ds_read_b128 v[212:215], v159 offset:37888
	ds_read_b128 v[216:219], v159 offset:38912
	ds_read_b128 v[224:227], v159 offset:39936
	global_load_lds_dwordx4 v150, s[6:7]
	s_mov_b32 m0, s15
	s_nop 0
	global_load_lds_dwordx4 v148, s[6:7]
	s_waitcnt vmcnt(8) lgkmcnt(0)
	s_barrier
	v_mfma_f32_16x16x32_bf16 v[144:147], v[160:163], v[192:195], v[144:147]
	v_mfma_f32_16x16x32_bf16 v[122:125], v[168:171], v[192:195], v[122:125]
	v_mfma_f32_16x16x32_bf16 v[118:121], v[160:163], v[200:203], v[118:121]
	v_mfma_f32_16x16x32_bf16 v[114:117], v[168:171], v[200:203], v[114:117]
	v_mfma_f32_16x16x32_bf16 v[102:105], v[160:163], v[208:211], v[102:105]
	v_mfma_f32_16x16x32_bf16 v[98:101], v[168:171], v[208:211], v[98:101]
	v_mfma_f32_16x16x32_bf16 v[86:89], v[160:163], v[216:219], v[86:89]
	v_mfma_f32_16x16x32_bf16 v[82:85], v[168:171], v[216:219], v[82:85]
	v_mfma_f32_16x16x32_bf16 v[144:147], v[164:167], v[196:199], v[144:147]
	v_mfma_f32_16x16x32_bf16 v[122:125], v[172:175], v[196:199], v[122:125]
	v_mfma_f32_16x16x32_bf16 v[118:121], v[164:167], v[204:207], v[118:121]
	v_mfma_f32_16x16x32_bf16 v[114:117], v[172:175], v[204:207], v[114:117]
	v_mfma_f32_16x16x32_bf16 v[102:105], v[164:167], v[212:215], v[102:105]
	v_mfma_f32_16x16x32_bf16 v[98:101], v[172:175], v[212:215], v[98:101]
	v_mfma_f32_16x16x32_bf16 v[86:89], v[164:167], v[224:227], v[86:89]
	v_mfma_f32_16x16x32_bf16 v[82:85], v[172:175], v[224:227], v[82:85]
	v_mfma_f32_16x16x32_bf16 v[110:113], v[176:179], v[192:195], v[110:113]
	v_mfma_f32_16x16x32_bf16 v[106:109], v[184:187], v[192:195], v[106:109]
	v_mfma_f32_16x16x32_bf16 v[94:97], v[176:179], v[200:203], v[94:97]
	v_mfma_f32_16x16x32_bf16 v[90:93], v[184:187], v[200:203], v[90:93]
	v_mfma_f32_16x16x32_bf16 v[78:81], v[176:179], v[208:211], v[78:81]
	v_mfma_f32_16x16x32_bf16 v[74:77], v[184:187], v[208:211], v[74:77]
	v_mfma_f32_16x16x32_bf16 v[70:73], v[176:179], v[216:219], v[70:73]
	v_mfma_f32_16x16x32_bf16 v[66:69], v[184:187], v[216:219], v[66:69]
	v_mfma_f32_16x16x32_bf16 v[110:113], v[180:183], v[196:199], v[110:113]
	v_mfma_f32_16x16x32_bf16 v[106:109], v[188:191], v[196:199], v[106:109]
	v_mfma_f32_16x16x32_bf16 v[94:97], v[180:183], v[204:207], v[94:97]
	v_mfma_f32_16x16x32_bf16 v[90:93], v[188:191], v[204:207], v[90:93]
	v_mfma_f32_16x16x32_bf16 v[78:81], v[180:183], v[212:215], v[78:81]
	v_mfma_f32_16x16x32_bf16 v[74:77], v[188:191], v[212:215], v[74:77]
	v_mfma_f32_16x16x32_bf16 v[70:73], v[180:183], v[224:227], v[70:73]
	v_mfma_f32_16x16x32_bf16 v[66:69], v[188:191], v[224:227], v[66:69]
	s_barrier
; #define PG8_STAGE(bufoff, gbase, voff) do { _Pragma("unroll") for (int _i = 0; _i < 2; ++_i) \
;         __builtin_amdgcn_global_load_lds((const unsigned*)((const char*)(gbase) + (voff)[_i]), (PG8_LAS unsigned*)(lds + (bufoff) + ldsw + _i * 8192), 16, 0, 0); } while (0)
; #define PG8_LDA(dst, b, h) do { _Pragma("unroll") for (int m = 0; m < 4; ++m) _Pragma("unroll") for (int k = 0; k < 2; ++k) dst[m][k] = *(const PG8_LAS bf16x8*)(lds + PG8_SA(b, h) + aoff + m * 2048 + k * 1024); } while (0)
; #define PG8_MMA(ai, bj, At, Bt) do { __builtin_amdgcn_s_setprio(1); _Pragma("unroll") for (int m = 0; m < 4; ++m) _Pragma("unroll") for (int n = 0; n < 2; ++n) _Pragma("unroll") for (int k = 0; k < 2; ++k) \
;         acc[ai][bj][m][n] = __builtin_amdgcn_mfma_f32_16x16x32_bf16(Bt[n][k], At[m][k], acc[ai][bj][m][n], 0, 0, 0); __builtin_amdgcn_s_setprio(0); } while (0)
; #define PG8_WAIT_V(n) asm volatile("s_waitcnt vmcnt(" #n ")" ::: "memory")
; #define PG8_WAIT_L(n) asm volatile("s_waitcnt lgkmcnt(" #n ")" ::: "memory")
; #define PG8_BAR __builtin_amdgcn_s_barrier()
; #define PG8_SCHED __builtin_amdgcn_sched_barrier(0)
; template <class Epi, class Sched, bool ALIGN_EPI = false, bool SP2 = false>
; __device__ __forceinline__ void gemm_phase(PG8_LAS unsigned char* lds, const Gemm g, const Sched& S, const Epi& E) {
;     ...
;             PG8_LDA(At, 1, 1); PG8_STAGE(PG8_SB(1, 0), b3, voffB); PG8_STAGE(PG8_SB(1, 1), b3 + hstep, voffB); PG8_STAGE(PG8_SA(1, 0), a3, voffA);
;             PG8_WAIT_V(8); PG8_WAIT_L(0); PG8_BAR; PG8_MMA(1, 0, At, B0); PG8_MMA(1, 1, At, B1); PG8_BAR; PG8_SCHED;
;     ...
;         if constexpr (ALIGN_EPI) { if (wr == 0) PG8_BAR; }
	s_add_i32 s6, s20, s9
	v_lshl_add_u64 v[228:229], v[228:229], 0, s[64:65]
	s_mov_b32 m0, s6
	ds_read_b128 v[192:195], v159 offset:49152
	ds_read_b128 v[196:199], v159 offset:50176
	ds_read_b128 v[200:203], v159 offset:51200
	ds_read_b128 v[204:207], v159 offset:52224
	ds_read_b128 v[208:211], v159 offset:53248
	ds_read_b128 v[212:215], v159 offset:54272
	ds_read_b128 v[216:219], v159 offset:55296
	ds_read_b128 v[224:227], v159 offset:56320
	global_load_lds_dwordx4 v[228:229], off
	s_add_i32 m0, s6, 0x2000
	s_add_u32 s4, s4, 0x80080
	v_lshl_add_u64 v[228:229], v[230:231], 0, s[64:65]
	s_addc_u32 s5, s5, 0
	s_add_i32 s6, s21, s9
	global_load_lds_dwordx4 v[228:229], off
	s_mov_b32 m0, s6
	s_nop 0
	global_load_lds_dwordx4 v0, s[4:5]
	s_add_i32 m0, s6, 0x2000
	s_nop 0
	global_load_lds_dwordx4 v126, s[4:5]
	s_mov_b32 m0, s17
	v_lshl_add_u64 v[228:229], v[232:233], 0, s[64:65]
	global_load_lds_dwordx4 v[228:229], off
	s_mov_b32 m0, s18
	v_lshl_add_u64 v[228:229], v[244:245], 0, s[64:65]
	global_load_lds_dwordx4 v[228:229], off
	s_waitcnt vmcnt(8) lgkmcnt(0)
	s_barrier
	v_mfma_f32_16x16x32_bf16 v[62:65], v[160:163], v[192:195], v[62:65]
	v_mfma_f32_16x16x32_bf16 v[58:61], v[168:171], v[192:195], v[58:61]
	v_mfma_f32_16x16x32_bf16 v[54:57], v[160:163], v[200:203], v[54:57]
	v_mfma_f32_16x16x32_bf16 v[50:53], v[168:171], v[200:203], v[50:53]
	v_mfma_f32_16x16x32_bf16 v[38:41], v[160:163], v[208:211], v[38:41]
	v_mfma_f32_16x16x32_bf16 v[34:37], v[168:171], v[208:211], v[34:37]
	v_mfma_f32_16x16x32_bf16 v[22:25], v[160:163], v[216:219], v[22:25]
	v_mfma_f32_16x16x32_bf16 v[18:21], v[168:171], v[216:219], v[18:21]
	v_mfma_f32_16x16x32_bf16 v[62:65], v[164:167], v[196:199], v[62:65]
	v_mfma_f32_16x16x32_bf16 v[58:61], v[172:175], v[196:199], v[58:61]
	v_mfma_f32_16x16x32_bf16 v[54:57], v[164:167], v[204:207], v[54:57]
	v_mfma_f32_16x16x32_bf16 v[50:53], v[172:175], v[204:207], v[50:53]
	v_mfma_f32_16x16x32_bf16 v[38:41], v[164:167], v[212:215], v[38:41]
	v_mfma_f32_16x16x32_bf16 v[34:37], v[172:175], v[212:215], v[34:37]
	v_mfma_f32_16x16x32_bf16 v[22:25], v[164:167], v[224:227], v[22:25]
	v_mfma_f32_16x16x32_bf16 v[18:21], v[172:175], v[224:227], v[18:21]
	v_mfma_f32_16x16x32_bf16 v[46:49], v[176:179], v[192:195], v[46:49]
	v_mfma_f32_16x16x32_bf16 v[42:45], v[184:187], v[192:195], v[42:45]
	v_mfma_f32_16x16x32_bf16 v[30:33], v[176:179], v[200:203], v[30:33]
	v_mfma_f32_16x16x32_bf16 v[26:29], v[184:187], v[200:203], v[26:29]
	v_mfma_f32_16x16x32_bf16 v[14:17], v[176:179], v[208:211], v[14:17]
	v_mfma_f32_16x16x32_bf16 v[10:13], v[184:187], v[208:211], v[10:13]
	v_mfma_f32_16x16x32_bf16 v[6:9], v[176:179], v[216:219], v[6:9]
	v_mfma_f32_16x16x32_bf16 v[2:5], v[184:187], v[216:219], v[2:5]
	v_mfma_f32_16x16x32_bf16 v[46:49], v[180:183], v[196:199], v[46:49]
	v_mfma_f32_16x16x32_bf16 v[42:45], v[188:191], v[196:199], v[42:45]
	v_mfma_f32_16x16x32_bf16 v[30:33], v[180:183], v[204:207], v[30:33]
	v_mfma_f32_16x16x32_bf16 v[26:29], v[188:191], v[204:207], v[26:29]
	v_mfma_f32_16x16x32_bf16 v[14:17], v[180:183], v[212:215], v[14:17]
	v_mfma_f32_16x16x32_bf16 v[10:13], v[188:191], v[212:215], v[10:13]
	v_mfma_f32_16x16x32_bf16 v[6:9], v[180:183], v[224:227], v[6:9]
	v_mfma_f32_16x16x32_bf16 v[2:5], v[188:191], v[224:227], v[2:5]
	s_barrier
	s_add_i32 s19, s19, 2
	s_add_u32 s0, s0, 0x100
	s_addc_u32 s1, s1, 0
	s_cmp_gt_u32 s19, 29
	s_cbranch_scc0 .LBB0_307
	s_cmpk_lt_u32 s8, 0x100
	s_cbranch_scc0 .LBB0_310
	s_barrier

; #define PG8_STAGE(bufoff, gbase, voff) do { _Pragma("unroll") for (int _i = 0; _i < 2; ++_i) \
;         __builtin_amdgcn_global_load_lds((const unsigned*)((const char*)(gbase) + (voff)[_i]), (PG8_LAS unsigned*)(lds + (bufoff) + ldsw + _i * 8192), 16, 0, 0); } while (0)
; #define PG8_LDA(dst, b, h) do { _Pragma("unroll") for (int m = 0; m < 4; ++m) _Pragma("unroll") for (int k = 0; k < 2; ++k) dst[m][k] = *(const PG8_LAS bf16x8*)(lds + PG8_SA(b, h) + aoff + m * 2048 + k * 1024); } while (0)
; #define PG8_LDB(dst, b, h) do { _Pragma("unroll") for (int n = 0; n < 2; ++n) _Pragma("unroll") for (int k = 0; k < 2; ++k) dst[n][k] = *(const PG8_LAS bf16x8*)(lds + PG8_SB(b, h) + boff + n * 2048 + k * 1024); } while (0)
; #define PG8_MMA(ai, bj, At, Bt) do { __builtin_amdgcn_s_setprio(1); _Pragma("unroll") for (int m = 0; m < 4; ++m) _Pragma("unroll") for (int n = 0; n < 2; ++n) _Pragma("unroll") for (int k = 0; k < 2; ++k) \
;         acc[ai][bj][m][n] = __builtin_amdgcn_mfma_f32_16x16x32_bf16(Bt[n][k], At[m][k], acc[ai][bj][m][n], 0, 0, 0); __builtin_amdgcn_s_setprio(0); } while (0)
; #define PG8_WAIT_V(n) asm volatile("s_waitcnt vmcnt(" #n ")" ::: "memory")
; #define PG8_WAIT_L(n) asm volatile("s_waitcnt lgkmcnt(" #n ")" ::: "memory")
; #define PG8_BAR __builtin_amdgcn_s_barrier()
; #define PG8_SCHED __builtin_amdgcn_sched_barrier(0)
; template <class Epi, class Sched, bool ALIGN_EPI = false, bool SP2 = false>
; __device__ __forceinline__ void gemm_phase(PG8_LAS unsigned char* lds, const Gemm g, const Sched& S, const Epi& E) {
;     ...
;             PG8_LDB(B0, 0, 0); PG8_LDB(B1, 0, 1); PG8_SCHED; PG8_LDA(At, 0, 0); PG8_STAGE(PG8_SA(1, 1), a1 + hstep, voffA);
;             PG8_WAIT_V(8); PG8_WAIT_L(0); PG8_BAR; PG8_MMA(0, 0, At, B0); PG8_MMA(0, 1, At, B1); PG8_BAR; PG8_SCHED;
;             PG8_LDA(At, 0, 1); PG8_STAGE(PG8_SB(0, 0), b2, voffB); PG8_STAGE(PG8_SB(0, 1), b2 + hstep, voffB); PG8_STAGE(PG8_SA(0, 0), a2, voffA);
;             PG8_WAIT_V(8); PG8_WAIT_L(0); PG8_BAR; PG8_MMA(1, 0, At, B0); PG8_MMA(1, 1, At, B1); PG8_BAR; PG8_SCHED;
.LBB0_733:
	s_add_u32 s22, s18, s20
	s_addc_u32 s23, s19, s21
	s_add_u32 s22, s22, 0x100
	s_addc_u32 s23, s23, 0
	s_add_u32 s26, s86, s20
	s_addc_u32 s27, s87, s21
	s_add_i32 s40, 0, 0x10000
	s_cmpk_eq_i32 s20, 0xf00
	s_cselect_b32 s25, s13, s23
	s_cselect_b32 s24, s82, s22
	s_cselect_b32 s23, s9, s27
	s_cselect_b32 s22, s83, s26
	s_add_i32 s41, 0, 0x14000
	v_add_u32_e32 v160, s40, v245
	v_add_u32_e32 v176, s41, v245
	ds_read_b128 v[148:151], v160
	ds_read_b128 v[152:155], v160 offset:1024
	ds_read_b128 v[156:159], v160 offset:2048
	ds_read_b128 v[160:163], v160 offset:3072
	ds_read_b128 v[164:167], v176
	ds_read_b128 v[168:171], v176 offset:1024
	ds_read_b128 v[172:175], v176 offset:2048
	ds_read_b128 v[176:179], v176 offset:3072
	v_lshl_add_u64 v[232:233], v[228:229], 0, s[20:21]
	s_add_i32 m0, s31, 0xc000
	ds_read_b128 v[180:183], v247
	ds_read_b128 v[184:187], v247 offset:1024
	ds_read_b128 v[188:191], v247 offset:2048
	ds_read_b128 v[192:195], v247 offset:3072
	ds_read_b128 v[196:199], v247 offset:4096
	ds_read_b128 v[200:203], v247 offset:5120
	ds_read_b128 v[204:207], v247 offset:6144
	ds_read_b128 v[208:211], v247 offset:7168
	global_load_lds_dwordx4 v[232:233], off
	s_add_i32 m0, s31, 0xe000
	v_lshl_add_u64 v[232:233], v[230:231], 0, s[20:21]
	global_load_lds_dwordx4 v[232:233], off
	s_waitcnt vmcnt(8) lgkmcnt(0)
	s_barrier
	v_mfma_f32_16x16x32_bf16 v[144:147], v[148:151], v[180:183], v[144:147]
	v_mfma_f32_16x16x32_bf16 v[122:125], v[156:159], v[180:183], v[122:125]
	v_mfma_f32_16x16x32_bf16 v[110:113], v[148:151], v[188:191], v[110:113]
	v_mfma_f32_16x16x32_bf16 v[106:109], v[156:159], v[188:191], v[106:109]
	v_mfma_f32_16x16x32_bf16 v[94:97], v[148:151], v[196:199], v[94:97]
	v_mfma_f32_16x16x32_bf16 v[90:93], v[156:159], v[196:199], v[90:93]
	v_mfma_f32_16x16x32_bf16 v[78:81], v[148:151], v[204:207], v[78:81]
	v_mfma_f32_16x16x32_bf16 v[74:77], v[156:159], v[204:207], v[74:77]
	v_mfma_f32_16x16x32_bf16 v[144:147], v[152:155], v[184:187], v[144:147]
	v_mfma_f32_16x16x32_bf16 v[122:125], v[160:163], v[184:187], v[122:125]
	v_mfma_f32_16x16x32_bf16 v[110:113], v[152:155], v[192:195], v[110:113]
	v_mfma_f32_16x16x32_bf16 v[106:109], v[160:163], v[192:195], v[106:109]
	v_mfma_f32_16x16x32_bf16 v[94:97], v[152:155], v[200:203], v[94:97]
	v_mfma_f32_16x16x32_bf16 v[90:93], v[160:163], v[200:203], v[90:93]
	v_mfma_f32_16x16x32_bf16 v[78:81], v[152:155], v[208:211], v[78:81]
	v_mfma_f32_16x16x32_bf16 v[74:77], v[160:163], v[208:211], v[74:77]
	v_mfma_f32_16x16x32_bf16 v[118:121], v[164:167], v[180:183], v[118:121]
	v_mfma_f32_16x16x32_bf16 v[114:117], v[172:175], v[180:183], v[114:117]
	v_mfma_f32_16x16x32_bf16 v[102:105], v[164:167], v[188:191], v[102:105]
	v_mfma_f32_16x16x32_bf16 v[98:101], v[172:175], v[188:191], v[98:101]
	v_mfma_f32_16x16x32_bf16 v[86:89], v[164:167], v[196:199], v[86:89]
	v_mfma_f32_16x16x32_bf16 v[82:85], v[172:175], v[196:199], v[82:85]
	v_mfma_f32_16x16x32_bf16 v[70:73], v[164:167], v[204:207], v[70:73]
	v_mfma_f32_16x16x32_bf16 v[66:69], v[172:175], v[204:207], v[66:69]
	v_mfma_f32_16x16x32_bf16 v[118:121], v[168:171], v[184:187], v[118:121]
	v_mfma_f32_16x16x32_bf16 v[114:117], v[176:179], v[184:187], v[114:117]
	v_mfma_f32_16x16x32_bf16 v[102:105], v[168:171], v[192:195], v[102:105]
	v_mfma_f32_16x16x32_bf16 v[98:101], v[176:179], v[192:195], v[98:101]
	v_mfma_f32_16x16x32_bf16 v[86:89], v[168:171], v[200:203], v[86:89]
	v_mfma_f32_16x16x32_bf16 v[82:85], v[176:179], v[200:203], v[82:85]
	v_mfma_f32_16x16x32_bf16 v[70:73], v[168:171], v[208:211], v[70:73]
	v_mfma_f32_16x16x32_bf16 v[66:69], v[176:179], v[208:211], v[66:69]
	s_barrier
	s_add_i32 s26, s40, s30
	v_lshl_add_u64 v[232:233], s[22:23], 0, v[0:1]
	s_mov_b32 m0, s26
	ds_read_b128 v[180:183], v247 offset:16384
	ds_read_b128 v[184:187], v247 offset:17408
	ds_read_b128 v[188:191], v247 offset:18432
	ds_read_b128 v[192:195], v247 offset:19456
	ds_read_b128 v[196:199], v247 offset:20480
	ds_read_b128 v[200:203], v247 offset:21504
	ds_read_b128 v[204:207], v247 offset:22528
	ds_read_b128 v[208:211], v247 offset:23552
	global_load_lds_dwordx4 v[232:233], off
	s_add_i32 m0, s26, 0x2000
	s_add_u32 s26, s22, 0x80000
	v_lshl_add_u64 v[248:249], s[22:23], 0, v[126:127]
	s_addc_u32 s27, s23, 0
	s_add_i32 s40, s41, s30
	global_load_lds_dwordx4 v[248:249], off
	s_mov_b32 m0, s40
	v_lshl_add_u64 v[220:221], s[24:25], 0, v[212:213]
	global_load_lds_dwordx4 v0, s[26:27]
	s_add_i32 m0, s40, 0x2000
	s_nop 0
	global_load_lds_dwordx4 v126, s[26:27]
	s_mov_b32 m0, s31
	v_lshl_add_u64 v[250:251], s[24:25], 0, v[214:215]
	global_load_lds_dwordx4 v[250:251], off
	s_mov_b32 m0, s34
	s_nop 0
	global_load_lds_dwordx4 v[220:221], off
	s_waitcnt vmcnt(8) lgkmcnt(0)
	s_barrier
; #define PG8_STAGE(bufoff, gbase, voff) do { _Pragma("unroll") for (int _i = 0; _i < 2; ++_i) \
;         __builtin_amdgcn_global_load_lds((const unsigned*)((const char*)(gbase) + (voff)[_i]), (PG8_LAS unsigned*)(lds + (bufoff) + ldsw + _i * 8192), 16, 0, 0); } while (0)
; #define PG8_LDA(dst, b, h) do { _Pragma("unroll") for (int m = 0; m < 4; ++m) _Pragma("unroll") for (int k = 0; k < 2; ++k) dst[m][k] = *(const PG8_LAS bf16x8*)(lds + PG8_SA(b, h) + aoff + m * 2048 + k * 1024); } while (0)
; #define PG8_LDB(dst, b, h) do { _Pragma("unroll") for (int n = 0; n < 2; ++n) _Pragma("unroll") for (int k = 0; k < 2; ++k) dst[n][k] = *(const PG8_LAS bf16x8*)(lds + PG8_SB(b, h) + boff + n * 2048 + k * 1024); } while (0)
; #define PG8_MMA(ai, bj, At, Bt) do { __builtin_amdgcn_s_setprio(1); _Pragma("unroll") for (int m = 0; m < 4; ++m) _Pragma("unroll") for (int n = 0; n < 2; ++n) _Pragma("unroll") for (int k = 0; k < 2; ++k) \
;         acc[ai][bj][m][n] = __builtin_amdgcn_mfma_f32_16x16x32_bf16(Bt[n][k], At[m][k], acc[ai][bj][m][n], 0, 0, 0); __builtin_amdgcn_s_setprio(0); } while (0)
; #define PG8_WAIT_V(n) asm volatile("s_waitcnt vmcnt(" #n ")" ::: "memory")
; #define PG8_WAIT_L(n) asm volatile("s_waitcnt lgkmcnt(" #n ")" ::: "memory")
; #define PG8_BAR __builtin_amdgcn_s_barrier()
; #define PG8_SCHED __builtin_amdgcn_sched_barrier(0)
; template <class Epi, class Sched, bool ALIGN_EPI = false, bool SP2 = false>
; __device__ __forceinline__ void gemm_phase(PG8_LAS unsigned char* lds, const Gemm g, const Sched& S, const Epi& E) {
;     ...
;             PG8_WAIT_V(8); PG8_WAIT_L(0); PG8_BAR; PG8_MMA(1, 0, At, B0); PG8_MMA(1, 1, At, B1); PG8_BAR; PG8_SCHED;
;             PG8_LDB(B0, 1, 0); PG8_LDB(B1, 1, 1); PG8_SCHED; PG8_LDA(At, 1, 0); PG8_STAGE(PG8_SA(0, 1), a2 + hstep, voffA);
;             PG8_WAIT_V(8); PG8_WAIT_L(0); PG8_BAR; PG8_MMA(0, 0, At, B0); PG8_MMA(0, 1, At, B1); PG8_BAR; PG8_SCHED;
	v_mfma_f32_16x16x32_bf16 v[62:65], v[148:151], v[180:183], v[62:65]
	v_mfma_f32_16x16x32_bf16 v[58:61], v[156:159], v[180:183], v[58:61]
	v_mfma_f32_16x16x32_bf16 v[46:49], v[148:151], v[188:191], v[46:49]
	v_mfma_f32_16x16x32_bf16 v[42:45], v[156:159], v[188:191], v[42:45]
	v_mfma_f32_16x16x32_bf16 v[30:33], v[148:151], v[196:199], v[30:33]
	v_mfma_f32_16x16x32_bf16 v[26:29], v[156:159], v[196:199], v[26:29]
	v_mfma_f32_16x16x32_bf16 v[14:17], v[148:151], v[204:207], v[14:17]
	v_mfma_f32_16x16x32_bf16 v[10:13], v[156:159], v[204:207], v[10:13]
	v_mfma_f32_16x16x32_bf16 v[62:65], v[152:155], v[184:187], v[62:65]
	v_mfma_f32_16x16x32_bf16 v[58:61], v[160:163], v[184:187], v[58:61]
	v_mfma_f32_16x16x32_bf16 v[46:49], v[152:155], v[192:195], v[46:49]
	v_mfma_f32_16x16x32_bf16 v[42:45], v[160:163], v[192:195], v[42:45]
	v_mfma_f32_16x16x32_bf16 v[30:33], v[152:155], v[200:203], v[30:33]
	v_mfma_f32_16x16x32_bf16 v[26:29], v[160:163], v[200:203], v[26:29]
	v_mfma_f32_16x16x32_bf16 v[14:17], v[152:155], v[208:211], v[14:17]
	v_mfma_f32_16x16x32_bf16 v[10:13], v[160:163], v[208:211], v[10:13]
	v_mfma_f32_16x16x32_bf16 v[54:57], v[164:167], v[180:183], v[54:57]
	v_mfma_f32_16x16x32_bf16 v[50:53], v[172:175], v[180:183], v[50:53]
	v_mfma_f32_16x16x32_bf16 v[38:41], v[164:167], v[188:191], v[38:41]
	v_mfma_f32_16x16x32_bf16 v[34:37], v[172:175], v[188:191], v[34:37]
	v_mfma_f32_16x16x32_bf16 v[22:25], v[164:167], v[196:199], v[22:25]
	v_mfma_f32_16x16x32_bf16 v[18:21], v[172:175], v[196:199], v[18:21]
	v_mfma_f32_16x16x32_bf16 v[6:9], v[164:167], v[204:207], v[6:9]
	v_mfma_f32_16x16x32_bf16 v[2:5], v[172:175], v[204:207], v[2:5]
	v_mfma_f32_16x16x32_bf16 v[54:57], v[168:171], v[184:187], v[54:57]
	v_mfma_f32_16x16x32_bf16 v[50:53], v[176:179], v[184:187], v[50:53]
	v_mfma_f32_16x16x32_bf16 v[38:41], v[168:171], v[192:195], v[38:41]
	v_mfma_f32_16x16x32_bf16 v[34:37], v[176:179], v[192:195], v[34:37]
	v_mfma_f32_16x16x32_bf16 v[22:25], v[168:171], v[200:203], v[22:25]
	v_mfma_f32_16x16x32_bf16 v[18:21], v[176:179], v[200:203], v[18:21]
	v_mfma_f32_16x16x32_bf16 v[6:9], v[168:171], v[208:211], v[6:9]
	v_mfma_f32_16x16x32_bf16 v[2:5], v[176:179], v[208:211], v[2:5]
	s_barrier
	s_add_i32 s26, 0, 0x18000
	s_add_i32 s27, 0, 0x1c000
	v_add_u32_e32 v160, s26, v245
	v_add_u32_e32 v176, s27, v245
	ds_read_b128 v[148:151], v160
	ds_read_b128 v[152:155], v160 offset:1024
	ds_read_b128 v[156:159], v160 offset:2048
	ds_read_b128 v[160:163], v160 offset:3072
	ds_read_b128 v[164:167], v176
	ds_read_b128 v[168:171], v176 offset:1024
	ds_read_b128 v[172:175], v176 offset:2048
	ds_read_b128 v[176:179], v176 offset:3072
	s_add_u32 s24, s24, 0x80000
	s_addc_u32 s25, s25, 0
	s_mov_b32 m0, s35
	ds_read_b128 v[180:183], v247 offset:32768
	ds_read_b128 v[184:187], v247 offset:33792
	ds_read_b128 v[188:191], v247 offset:34816
	ds_read_b128 v[192:195], v247 offset:35840
	ds_read_b128 v[196:199], v247 offset:36864
	ds_read_b128 v[200:203], v247 offset:37888
	ds_read_b128 v[204:207], v247 offset:38912
	ds_read_b128 v[208:211], v247 offset:39936
	global_load_lds_dwordx4 v214, s[24:25]
	s_mov_b32 m0, s36
	s_nop 0
	global_load_lds_dwordx4 v212, s[24:25]
	s_waitcnt vmcnt(8) lgkmcnt(0)
	s_barrier
	v_mfma_f32_16x16x32_bf16 v[144:147], v[148:151], v[180:183], v[144:147]
	v_mfma_f32_16x16x32_bf16 v[122:125], v[156:159], v[180:183], v[122:125]
	v_mfma_f32_16x16x32_bf16 v[110:113], v[148:151], v[188:191], v[110:113]
	v_mfma_f32_16x16x32_bf16 v[106:109], v[156:159], v[188:191], v[106:109]
	v_mfma_f32_16x16x32_bf16 v[94:97], v[148:151], v[196:199], v[94:97]
	v_mfma_f32_16x16x32_bf16 v[90:93], v[156:159], v[196:199], v[90:93]
	v_mfma_f32_16x16x32_bf16 v[78:81], v[148:151], v[204:207], v[78:81]
	v_mfma_f32_16x16x32_bf16 v[74:77], v[156:159], v[204:207], v[74:77]
	v_mfma_f32_16x16x32_bf16 v[144:147], v[152:155], v[184:187], v[144:147]
	v_mfma_f32_16x16x32_bf16 v[122:125], v[160:163], v[184:187], v[122:125]
	v_mfma_f32_16x16x32_bf16 v[110:113], v[152:155], v[192:195], v[110:113]
	v_mfma_f32_16x16x32_bf16 v[106:109], v[160:163], v[192:195], v[106:109]
	v_mfma_f32_16x16x32_bf16 v[94:97], v[152:155], v[200:203], v[94:97]
	v_mfma_f32_16x16x32_bf16 v[90:93], v[160:163], v[200:203], v[90:93]
	v_mfma_f32_16x16x32_bf16 v[78:81], v[152:155], v[208:211], v[78:81]
	v_mfma_f32_16x16x32_bf16 v[74:77], v[160:163], v[208:211], v[74:77]
	v_mfma_f32_16x16x32_bf16 v[118:121], v[164:167], v[180:183], v[118:121]
	v_mfma_f32_16x16x32_bf16 v[114:117], v[172:175], v[180:183], v[114:117]
	v_mfma_f32_16x16x32_bf16 v[102:105], v[164:167], v[188:191], v[102:105]
	v_mfma_f32_16x16x32_bf16 v[98:101], v[172:175], v[188:191], v[98:101]
	v_mfma_f32_16x16x32_bf16 v[86:89], v[164:167], v[196:199], v[86:89]
	v_mfma_f32_16x16x32_bf16 v[82:85], v[172:175], v[196:199], v[82:85]
	v_mfma_f32_16x16x32_bf16 v[70:73], v[164:167], v[204:207], v[70:73]
	v_mfma_f32_16x16x32_bf16 v[66:69], v[172:175], v[204:207], v[66:69]
	v_mfma_f32_16x16x32_bf16 v[118:121], v[168:171], v[184:187], v[118:121]
	v_mfma_f32_16x16x32_bf16 v[114:117], v[176:179], v[184:187], v[114:117]
	v_mfma_f32_16x16x32_bf16 v[102:105], v[168:171], v[192:195], v[102:105]
	v_mfma_f32_16x16x32_bf16 v[98:101], v[176:179], v[192:195], v[98:101]
	v_mfma_f32_16x16x32_bf16 v[86:89], v[168:171], v[200:203], v[86:89]
	v_mfma_f32_16x16x32_bf16 v[82:85], v[176:179], v[200:203], v[82:85]
	v_mfma_f32_16x16x32_bf16 v[70:73], v[168:171], v[208:211], v[70:73]
	v_mfma_f32_16x16x32_bf16 v[66:69], v[176:179], v[208:211], v[66:69]
	s_barrier
; #define PG8_STAGE(bufoff, gbase, voff) do { _Pragma("unroll") for (int _i = 0; _i < 2; ++_i) \
;         __builtin_amdgcn_global_load_lds((const unsigned*)((const char*)(gbase) + (voff)[_i]), (PG8_LAS unsigned*)(lds + (bufoff) + ldsw + _i * 8192), 16, 0, 0); } while (0)
; #define PG8_LDA(dst, b, h) do { _Pragma("unroll") for (int m = 0; m < 4; ++m) _Pragma("unroll") for (int k = 0; k < 2; ++k) dst[m][k] = *(const PG8_LAS bf16x8*)(lds + PG8_SA(b, h) + aoff + m * 2048 + k * 1024); } while (0)
; #define PG8_MMA(ai, bj, At, Bt) do { __builtin_amdgcn_s_setprio(1); _Pragma("unroll") for (int m = 0; m < 4; ++m) _Pragma("unroll") for (int n = 0; n < 2; ++n) _Pragma("unroll") for (int k = 0; k < 2; ++k) \
;         acc[ai][bj][m][n] = __builtin_amdgcn_mfma_f32_16x16x32_bf16(Bt[n][k], At[m][k], acc[ai][bj][m][n], 0, 0, 0); __builtin_amdgcn_s_setprio(0); } while (0)
; #define PG8_WAIT_V(n) asm volatile("s_waitcnt vmcnt(" #n ")" ::: "memory")
; #define PG8_WAIT_L(n) asm volatile("s_waitcnt lgkmcnt(" #n ")" ::: "memory")
; #define PG8_BAR __builtin_amdgcn_s_barrier()
; #define PG8_SCHED __builtin_amdgcn_sched_barrier(0)
; template <class Epi, class Sched, bool ALIGN_EPI = false, bool SP2 = false>
; __device__ __forceinline__ void gemm_phase(PG8_LAS unsigned char* lds, const Gemm g, const Sched& S, const Epi& E) {
;     ...
;             PG8_LDA(At, 1, 1); PG8_STAGE(PG8_SB(1, 0), b3, voffB); PG8_STAGE(PG8_SB(1, 1), b3 + hstep, voffB); PG8_STAGE(PG8_SA(1, 0), a3, voffA);
;             PG8_WAIT_V(8); PG8_WAIT_L(0); PG8_BAR; PG8_MMA(1, 0, At, B0); PG8_MMA(1, 1, At, B1); PG8_BAR; PG8_SCHED;
	s_add_i32 s24, s26, s30
	v_lshl_add_u64 v[222:223], v[232:233], 0, s[64:65]
	s_mov_b32 m0, s24
	ds_read_b128 v[180:183], v247 offset:49152
	ds_read_b128 v[184:187], v247 offset:50176
	ds_read_b128 v[188:191], v247 offset:51200
	ds_read_b128 v[192:195], v247 offset:52224
	ds_read_b128 v[196:199], v247 offset:53248
	ds_read_b128 v[200:203], v247 offset:54272
	ds_read_b128 v[204:207], v247 offset:55296
	ds_read_b128 v[208:211], v247 offset:56320
	global_load_lds_dwordx4 v[222:223], off
	s_add_i32 m0, s24, 0x2000
	s_add_u32 s22, s22, 0x80080
	v_lshl_add_u64 v[222:223], v[248:249], 0, s[64:65]
	s_addc_u32 s23, s23, 0
	s_add_i32 s24, s27, s30
	global_load_lds_dwordx4 v[222:223], off
	s_mov_b32 m0, s24
	v_lshl_add_u64 v[220:221], v[220:221], 0, s[64:65]
	global_load_lds_dwordx4 v0, s[22:23]
	s_add_i32 m0, s24, 0x2000
	s_nop 0
	global_load_lds_dwordx4 v126, s[22:23]
	s_mov_b32 m0, s37
	v_lshl_add_u64 v[222:223], v[250:251], 0, s[64:65]
	global_load_lds_dwordx4 v[222:223], off
	s_mov_b32 m0, s84
	s_nop 0
	global_load_lds_dwordx4 v[220:221], off
	s_waitcnt vmcnt(8) lgkmcnt(0)
	s_barrier
	v_mfma_f32_16x16x32_bf16 v[62:65], v[148:151], v[180:183], v[62:65]
	v_mfma_f32_16x16x32_bf16 v[58:61], v[156:159], v[180:183], v[58:61]
	v_mfma_f32_16x16x32_bf16 v[46:49], v[148:151], v[188:191], v[46:49]
	v_mfma_f32_16x16x32_bf16 v[42:45], v[156:159], v[188:191], v[42:45]
	v_mfma_f32_16x16x32_bf16 v[30:33], v[148:151], v[196:199], v[30:33]
	v_mfma_f32_16x16x32_bf16 v[26:29], v[156:159], v[196:199], v[26:29]
	v_mfma_f32_16x16x32_bf16 v[14:17], v[148:151], v[204:207], v[14:17]
	v_mfma_f32_16x16x32_bf16 v[10:13], v[156:159], v[204:207], v[10:13]
	v_mfma_f32_16x16x32_bf16 v[62:65], v[152:155], v[184:187], v[62:65]
	v_mfma_f32_16x16x32_bf16 v[58:61], v[160:163], v[184:187], v[58:61]
	v_mfma_f32_16x16x32_bf16 v[46:49], v[152:155], v[192:195], v[46:49]
	v_mfma_f32_16x16x32_bf16 v[42:45], v[160:163], v[192:195], v[42:45]
	v_mfma_f32_16x16x32_bf16 v[30:33], v[152:155], v[200:203], v[30:33]
	v_mfma_f32_16x16x32_bf16 v[26:29], v[160:163], v[200:203], v[26:29]
	v_mfma_f32_16x16x32_bf16 v[14:17], v[152:155], v[208:211], v[14:17]
	v_mfma_f32_16x16x32_bf16 v[10:13], v[160:163], v[208:211], v[10:13]
	v_mfma_f32_16x16x32_bf16 v[54:57], v[164:167], v[180:183], v[54:57]
	v_mfma_f32_16x16x32_bf16 v[50:53], v[172:175], v[180:183], v[50:53]
	v_mfma_f32_16x16x32_bf16 v[38:41], v[164:167], v[188:191], v[38:41]
	v_mfma_f32_16x16x32_bf16 v[34:37], v[172:175], v[188:191], v[34:37]
	v_mfma_f32_16x16x32_bf16 v[22:25], v[164:167], v[196:199], v[22:25]
	v_mfma_f32_16x16x32_bf16 v[18:21], v[172:175], v[196:199], v[18:21]
	v_mfma_f32_16x16x32_bf16 v[6:9], v[164:167], v[204:207], v[6:9]
	v_mfma_f32_16x16x32_bf16 v[2:5], v[172:175], v[204:207], v[2:5]
	v_mfma_f32_16x16x32_bf16 v[54:57], v[168:171], v[184:187], v[54:57]
	v_mfma_f32_16x16x32_bf16 v[50:53], v[176:179], v[184:187], v[50:53]
	v_mfma_f32_16x16x32_bf16 v[38:41], v[168:171], v[192:195], v[38:41]
	v_mfma_f32_16x16x32_bf16 v[34:37], v[176:179], v[192:195], v[34:37]
	v_mfma_f32_16x16x32_bf16 v[22:25], v[168:171], v[200:203], v[22:25]
	v_mfma_f32_16x16x32_bf16 v[18:21], v[176:179], v[200:203], v[18:21]
	v_mfma_f32_16x16x32_bf16 v[6:9], v[168:171], v[208:211], v[6:9]
	v_mfma_f32_16x16x32_bf16 v[2:5], v[176:179], v[208:211], v[2:5]
	s_barrier
	s_add_i32 s22, s76, 2
	s_add_u32 s20, s20, 0x100
	s_addc_u32 s21, s21, 0
	s_cmp_gt_u32 s76, 29
	s_mov_b32 s76, s22
	s_cbranch_scc1 .LBB0_742

; #define PG8_STAGE(bufoff, gbase, voff) do { _Pragma("unroll") for (int _i = 0; _i < 2; ++_i) \
;         __builtin_amdgcn_global_load_lds((const unsigned*)((const char*)(gbase) + (voff)[_i]), (PG8_LAS unsigned*)(lds + (bufoff) + ldsw + _i * 8192), 16, 0, 0); } while (0)
; #define PG8_LDA(dst, b, h) do { _Pragma("unroll") for (int m = 0; m < 4; ++m) _Pragma("unroll") for (int k = 0; k < 2; ++k) dst[m][k] = *(const PG8_LAS bf16x8*)(lds + PG8_SA(b, h) + aoff + m * 2048 + k * 1024); } while (0)
; #define PG8_LDB(dst, b, h) do { _Pragma("unroll") for (int n = 0; n < 2; ++n) _Pragma("unroll") for (int k = 0; k < 2; ++k) dst[n][k] = *(const PG8_LAS bf16x8*)(lds + PG8_SB(b, h) + boff + n * 2048 + k * 1024); } while (0)
; #define PG8_MMA(ai, bj, At, Bt) do { __builtin_amdgcn_s_setprio(1); _Pragma("unroll") for (int m = 0; m < 4; ++m) _Pragma("unroll") for (int n = 0; n < 2; ++n) _Pragma("unroll") for (int k = 0; k < 2; ++k) \
;         acc[ai][bj][m][n] = __builtin_amdgcn_mfma_f32_16x16x32_bf16(Bt[n][k], At[m][k], acc[ai][bj][m][n], 0, 0, 0); __builtin_amdgcn_s_setprio(0); } while (0)
; #define PG8_WAIT_V(n) asm volatile("s_waitcnt vmcnt(" #n ")" ::: "memory")
; #define PG8_WAIT_L(n) asm volatile("s_waitcnt lgkmcnt(" #n ")" ::: "memory")
; #define PG8_BAR __builtin_amdgcn_s_barrier()
; #define PG8_SCHED __builtin_amdgcn_sched_barrier(0)
; template <class Epi, class Sched, bool ALIGN_EPI = false, bool SP2 = false>
; __device__ __forceinline__ void gemm_phase(PG8_LAS unsigned char* lds, const Gemm g, const Sched& S, const Epi& E) {
;     ...
;             PG8_LDB(B0, 0, 0); PG8_LDB(B1, 0, 1); PG8_SCHED; PG8_LDA(At, 0, 0); PG8_STAGE(PG8_SA(1, 1), a1 + hstep, voffA);
;             PG8_WAIT_V(8); PG8_WAIT_L(0); PG8_BAR; PG8_MMA(0, 0, At, B0); PG8_MMA(0, 1, At, B1); PG8_BAR; PG8_SCHED;
;             PG8_LDA(At, 0, 1); PG8_STAGE(PG8_SB(0, 0), b2, voffB); PG8_STAGE(PG8_SB(0, 1), b2 + hstep, voffB); PG8_STAGE(PG8_SA(0, 0), a2, voffA);
;             PG8_WAIT_V(8); PG8_WAIT_L(0); PG8_BAR; PG8_MMA(1, 0, At, B0); PG8_MMA(1, 1, At, B1); PG8_BAR; PG8_SCHED;
.LBB0_808:
	s_add_u32 s28, s8, 0xfff80080
	s_addc_u32 s29, s9, -1
	s_add_i32 s48, 0, 0x10000
	s_cmp_eq_u32 s87, 28
	s_cselect_b32 s31, s23, s29
	s_cselect_b32 s30, s67, s28
	v_add_u32_e32 v160, s48, v163
	s_cselect_b32 s29, s21, s86
	s_cselect_b32 s28, s81, s83
	s_add_i32 s91, 0, 0x14000
	ds_read_b128 v[152:155], v160
	ds_read_b128 v[156:159], v160 offset:1024
	ds_read_b128 v[166:169], v160 offset:2048
	ds_read_b128 v[170:173], v160 offset:3072
	v_add_u32_e32 v160, s91, v163
	ds_read_b128 v[174:177], v160
	ds_read_b128 v[178:181], v160 offset:1024
	ds_read_b128 v[182:185], v160 offset:2048
	ds_read_b128 v[186:189], v160 offset:3072
	s_add_i32 m0, s13, 0xc000
	ds_read_b128 v[190:193], v165
	ds_read_b128 v[194:197], v165 offset:1024
	ds_read_b128 v[198:201], v165 offset:2048
	ds_read_b128 v[202:205], v165 offset:3072
	ds_read_b128 v[206:209], v165 offset:4096
	ds_read_b128 v[210:213], v165 offset:5120
	ds_read_b128 v[214:217], v165 offset:6144
	ds_read_b128 v[224:227], v165 offset:7168
	global_load_lds_dwordx4 v148, s[8:9]
	s_add_i32 m0, s13, 0xe000
	s_nop 0
	global_load_lds_dwordx4 v150, s[8:9]
	s_waitcnt vmcnt(8) lgkmcnt(0)
	s_barrier
	v_mfma_f32_16x16x32_bf16 v[144:147], v[152:155], v[190:193], v[144:147]
	v_mfma_f32_16x16x32_bf16 v[122:125], v[166:169], v[190:193], v[122:125]
	v_mfma_f32_16x16x32_bf16 v[110:113], v[152:155], v[198:201], v[110:113]
	v_mfma_f32_16x16x32_bf16 v[106:109], v[166:169], v[198:201], v[106:109]
	v_mfma_f32_16x16x32_bf16 v[94:97], v[152:155], v[206:209], v[94:97]
	v_mfma_f32_16x16x32_bf16 v[90:93], v[166:169], v[206:209], v[90:93]
	v_mfma_f32_16x16x32_bf16 v[78:81], v[152:155], v[214:217], v[78:81]
	v_mfma_f32_16x16x32_bf16 v[74:77], v[166:169], v[214:217], v[74:77]
	v_mfma_f32_16x16x32_bf16 v[144:147], v[156:159], v[194:197], v[144:147]
	v_mfma_f32_16x16x32_bf16 v[122:125], v[170:173], v[194:197], v[122:125]
	v_mfma_f32_16x16x32_bf16 v[110:113], v[156:159], v[202:205], v[110:113]
	v_mfma_f32_16x16x32_bf16 v[106:109], v[170:173], v[202:205], v[106:109]
	v_mfma_f32_16x16x32_bf16 v[94:97], v[156:159], v[210:213], v[94:97]
	v_mfma_f32_16x16x32_bf16 v[90:93], v[170:173], v[210:213], v[90:93]
	v_mfma_f32_16x16x32_bf16 v[78:81], v[156:159], v[224:227], v[78:81]
	v_mfma_f32_16x16x32_bf16 v[74:77], v[170:173], v[224:227], v[74:77]
	v_mfma_f32_16x16x32_bf16 v[118:121], v[174:177], v[190:193], v[118:121]
	v_mfma_f32_16x16x32_bf16 v[114:117], v[182:185], v[190:193], v[114:117]
	v_mfma_f32_16x16x32_bf16 v[102:105], v[174:177], v[198:201], v[102:105]
	v_mfma_f32_16x16x32_bf16 v[98:101], v[182:185], v[198:201], v[98:101]
	v_mfma_f32_16x16x32_bf16 v[86:89], v[174:177], v[206:209], v[86:89]
	v_mfma_f32_16x16x32_bf16 v[82:85], v[182:185], v[206:209], v[82:85]
	v_mfma_f32_16x16x32_bf16 v[70:73], v[174:177], v[214:217], v[70:73]
	v_mfma_f32_16x16x32_bf16 v[66:69], v[182:185], v[214:217], v[66:69]
	v_mfma_f32_16x16x32_bf16 v[118:121], v[178:181], v[194:197], v[118:121]
	v_mfma_f32_16x16x32_bf16 v[114:117], v[186:189], v[194:197], v[114:117]
	v_mfma_f32_16x16x32_bf16 v[102:105], v[178:181], v[202:205], v[102:105]
	v_mfma_f32_16x16x32_bf16 v[98:101], v[186:189], v[202:205], v[98:101]
	v_mfma_f32_16x16x32_bf16 v[86:89], v[178:181], v[210:213], v[86:89]
	v_mfma_f32_16x16x32_bf16 v[82:85], v[186:189], v[210:213], v[82:85]
	v_mfma_f32_16x16x32_bf16 v[70:73], v[178:181], v[224:227], v[70:73]
	v_mfma_f32_16x16x32_bf16 v[66:69], v[186:189], v[224:227], v[66:69]
	s_barrier
	s_add_i32 s48, s48, s12
	v_lshl_add_u64 v[160:161], s[28:29], 0, v[0:1]
	s_mov_b32 m0, s48
	ds_read_b128 v[190:193], v165 offset:16384
	ds_read_b128 v[194:197], v165 offset:17408
	ds_read_b128 v[198:201], v165 offset:18432
	ds_read_b128 v[202:205], v165 offset:19456
	ds_read_b128 v[206:209], v165 offset:20480
	ds_read_b128 v[210:213], v165 offset:21504
	ds_read_b128 v[214:217], v165 offset:22528
	ds_read_b128 v[224:227], v165 offset:23552
	global_load_lds_dwordx4 v[160:161], off
	s_add_i32 m0, s48, 0x2000
	s_add_u32 vcc_lo, s28, 0x80000
	v_lshl_add_u64 v[218:219], s[28:29], 0, v[126:127]
	s_addc_u32 vcc_hi, s29, 0
	s_add_i32 s48, s91, s12
	global_load_lds_dwordx4 v[218:219], off
	v_lshl_add_u64 v[220:221], vcc, 0, v[0:1]
	s_mov_b32 m0, s48
	v_lshl_add_u64 v[222:223], s[30:31], 0, v[126:127]
	global_load_lds_dwordx4 v[220:221], off
	s_add_i32 m0, s48, 0x2000
	v_lshl_add_u64 v[220:221], vcc, 0, v[126:127]
	global_load_lds_dwordx4 v[220:221], off
	s_mov_b32 m0, s13
	v_lshl_add_u64 v[220:221], s[30:31], 0, v[0:1]
	global_load_lds_dwordx4 v[220:221], off
	s_mov_b32 m0, s34
	s_nop 0
	global_load_lds_dwordx4 v[222:223], off
	s_waitcnt vmcnt(8) lgkmcnt(0)
	s_barrier
; #define PG8_STAGE(bufoff, gbase, voff) do { _Pragma("unroll") for (int _i = 0; _i < 2; ++_i) \
;         __builtin_amdgcn_global_load_lds((const unsigned*)((const char*)(gbase) + (voff)[_i]), (PG8_LAS unsigned*)(lds + (bufoff) + ldsw + _i * 8192), 16, 0, 0); } while (0)
; #define PG8_LDA(dst, b, h) do { _Pragma("unroll") for (int m = 0; m < 4; ++m) _Pragma("unroll") for (int k = 0; k < 2; ++k) dst[m][k] = *(const PG8_LAS bf16x8*)(lds + PG8_SA(b, h) + aoff + m * 2048 + k * 1024); } while (0)
; #define PG8_LDB(dst, b, h) do { _Pragma("unroll") for (int n = 0; n < 2; ++n) _Pragma("unroll") for (int k = 0; k < 2; ++k) dst[n][k] = *(const PG8_LAS bf16x8*)(lds + PG8_SB(b, h) + boff + n * 2048 + k * 1024); } while (0)
; #define PG8_MMA(ai, bj, At, Bt) do { __builtin_amdgcn_s_setprio(1); _Pragma("unroll") for (int m = 0; m < 4; ++m) _Pragma("unroll") for (int n = 0; n < 2; ++n) _Pragma("unroll") for (int k = 0; k < 2; ++k) \
;         acc[ai][bj][m][n] = __builtin_amdgcn_mfma_f32_16x16x32_bf16(Bt[n][k], At[m][k], acc[ai][bj][m][n], 0, 0, 0); __builtin_amdgcn_s_setprio(0); } while (0)
; #define PG8_WAIT_V(n) asm volatile("s_waitcnt vmcnt(" #n ")" ::: "memory")
; #define PG8_WAIT_L(n) asm volatile("s_waitcnt lgkmcnt(" #n ")" ::: "memory")
; #define PG8_BAR __builtin_amdgcn_s_barrier()
; #define PG8_SCHED __builtin_amdgcn_sched_barrier(0)
; template <class Epi, class Sched, bool ALIGN_EPI = false, bool SP2 = false>
; __device__ __forceinline__ void gemm_phase(PG8_LAS unsigned char* lds, const Gemm g, const Sched& S, const Epi& E) {
;     ...
;             PG8_WAIT_V(8); PG8_WAIT_L(0); PG8_BAR; PG8_MMA(1, 0, At, B0); PG8_MMA(1, 1, At, B1); PG8_BAR; PG8_SCHED;
;             PG8_LDB(B0, 1, 0); PG8_LDB(B1, 1, 1); PG8_SCHED; PG8_LDA(At, 1, 0); PG8_STAGE(PG8_SA(0, 1), a2 + hstep, voffA);
;             PG8_WAIT_V(8); PG8_WAIT_L(0); PG8_BAR; PG8_MMA(0, 0, At, B0); PG8_MMA(0, 1, At, B1); PG8_BAR; PG8_SCHED;
	v_mfma_f32_16x16x32_bf16 v[62:65], v[152:155], v[190:193], v[62:65]
	v_mfma_f32_16x16x32_bf16 v[58:61], v[166:169], v[190:193], v[58:61]
	v_mfma_f32_16x16x32_bf16 v[46:49], v[152:155], v[198:201], v[46:49]
	v_mfma_f32_16x16x32_bf16 v[42:45], v[166:169], v[198:201], v[42:45]
	v_mfma_f32_16x16x32_bf16 v[30:33], v[152:155], v[206:209], v[30:33]
	v_mfma_f32_16x16x32_bf16 v[26:29], v[166:169], v[206:209], v[26:29]
	v_mfma_f32_16x16x32_bf16 v[14:17], v[152:155], v[214:217], v[14:17]
	v_mfma_f32_16x16x32_bf16 v[10:13], v[166:169], v[214:217], v[10:13]
	v_mfma_f32_16x16x32_bf16 v[62:65], v[156:159], v[194:197], v[62:65]
	v_mfma_f32_16x16x32_bf16 v[58:61], v[170:173], v[194:197], v[58:61]
	v_mfma_f32_16x16x32_bf16 v[46:49], v[156:159], v[202:205], v[46:49]
	v_mfma_f32_16x16x32_bf16 v[42:45], v[170:173], v[202:205], v[42:45]
	v_mfma_f32_16x16x32_bf16 v[30:33], v[156:159], v[210:213], v[30:33]
	v_mfma_f32_16x16x32_bf16 v[26:29], v[170:173], v[210:213], v[26:29]
	v_mfma_f32_16x16x32_bf16 v[14:17], v[156:159], v[224:227], v[14:17]
	v_mfma_f32_16x16x32_bf16 v[10:13], v[170:173], v[224:227], v[10:13]
	v_mfma_f32_16x16x32_bf16 v[54:57], v[174:177], v[190:193], v[54:57]
	v_mfma_f32_16x16x32_bf16 v[50:53], v[182:185], v[190:193], v[50:53]
	v_mfma_f32_16x16x32_bf16 v[38:41], v[174:177], v[198:201], v[38:41]
	v_mfma_f32_16x16x32_bf16 v[34:37], v[182:185], v[198:201], v[34:37]
	v_mfma_f32_16x16x32_bf16 v[22:25], v[174:177], v[206:209], v[22:25]
	v_mfma_f32_16x16x32_bf16 v[18:21], v[182:185], v[206:209], v[18:21]
	v_mfma_f32_16x16x32_bf16 v[6:9], v[174:177], v[214:217], v[6:9]
	v_mfma_f32_16x16x32_bf16 v[2:5], v[182:185], v[214:217], v[2:5]
	v_mfma_f32_16x16x32_bf16 v[54:57], v[178:181], v[194:197], v[54:57]
	v_mfma_f32_16x16x32_bf16 v[50:53], v[186:189], v[194:197], v[50:53]
	v_mfma_f32_16x16x32_bf16 v[38:41], v[178:181], v[202:205], v[38:41]
	v_mfma_f32_16x16x32_bf16 v[34:37], v[186:189], v[202:205], v[34:37]
	v_mfma_f32_16x16x32_bf16 v[22:25], v[178:181], v[210:213], v[22:25]
	v_mfma_f32_16x16x32_bf16 v[18:21], v[186:189], v[210:213], v[18:21]
	v_mfma_f32_16x16x32_bf16 v[6:9], v[178:181], v[224:227], v[6:9]
	v_mfma_f32_16x16x32_bf16 v[2:5], v[186:189], v[224:227], v[2:5]
	s_barrier
	s_add_i32 s48, 0, 0x18000
	s_add_i32 s91, 0, 0x1c000
	v_add_u32_e32 v170, s48, v163
	v_add_u32_e32 v186, s91, v163
	ds_read_b128 v[152:155], v170
	ds_read_b128 v[156:159], v170 offset:1024
	ds_read_b128 v[166:169], v170 offset:2048
	ds_read_b128 v[170:173], v170 offset:3072
	ds_read_b128 v[174:177], v186
	ds_read_b128 v[178:181], v186 offset:1024
	ds_read_b128 v[182:185], v186 offset:2048
	ds_read_b128 v[186:189], v186 offset:3072
	s_add_u32 s30, s30, 0x80000
	s_addc_u32 s31, s31, 0
	s_mov_b32 m0, s35
	ds_read_b128 v[190:193], v165 offset:32768
	ds_read_b128 v[194:197], v165 offset:33792
	ds_read_b128 v[198:201], v165 offset:34816
	ds_read_b128 v[202:205], v165 offset:35840
	ds_read_b128 v[206:209], v165 offset:36864
	ds_read_b128 v[210:213], v165 offset:37888
	ds_read_b128 v[214:217], v165 offset:38912
	ds_read_b128 v[224:227], v165 offset:39936
	global_load_lds_dwordx4 v0, s[30:31]
	s_mov_b32 m0, s42
	s_nop 0
	global_load_lds_dwordx4 v126, s[30:31]
	s_waitcnt vmcnt(8) lgkmcnt(0)
	s_barrier
	v_mfma_f32_16x16x32_bf16 v[144:147], v[152:155], v[190:193], v[144:147]
	v_mfma_f32_16x16x32_bf16 v[122:125], v[166:169], v[190:193], v[122:125]
	v_mfma_f32_16x16x32_bf16 v[110:113], v[152:155], v[198:201], v[110:113]
	v_mfma_f32_16x16x32_bf16 v[106:109], v[166:169], v[198:201], v[106:109]
	v_mfma_f32_16x16x32_bf16 v[94:97], v[152:155], v[206:209], v[94:97]
	v_mfma_f32_16x16x32_bf16 v[90:93], v[166:169], v[206:209], v[90:93]
	v_mfma_f32_16x16x32_bf16 v[78:81], v[152:155], v[214:217], v[78:81]
	v_mfma_f32_16x16x32_bf16 v[74:77], v[166:169], v[214:217], v[74:77]
	v_mfma_f32_16x16x32_bf16 v[144:147], v[156:159], v[194:197], v[144:147]
	v_mfma_f32_16x16x32_bf16 v[122:125], v[170:173], v[194:197], v[122:125]
	v_mfma_f32_16x16x32_bf16 v[110:113], v[156:159], v[202:205], v[110:113]
	v_mfma_f32_16x16x32_bf16 v[106:109], v[170:173], v[202:205], v[106:109]
	v_mfma_f32_16x16x32_bf16 v[94:97], v[156:159], v[210:213], v[94:97]
	v_mfma_f32_16x16x32_bf16 v[90:93], v[170:173], v[210:213], v[90:93]
	v_mfma_f32_16x16x32_bf16 v[78:81], v[156:159], v[224:227], v[78:81]
	v_mfma_f32_16x16x32_bf16 v[74:77], v[170:173], v[224:227], v[74:77]
	v_mfma_f32_16x16x32_bf16 v[118:121], v[174:177], v[190:193], v[118:121]
	v_mfma_f32_16x16x32_bf16 v[114:117], v[182:185], v[190:193], v[114:117]
	v_mfma_f32_16x16x32_bf16 v[102:105], v[174:177], v[198:201], v[102:105]
	v_mfma_f32_16x16x32_bf16 v[98:101], v[182:185], v[198:201], v[98:101]
	v_mfma_f32_16x16x32_bf16 v[86:89], v[174:177], v[206:209], v[86:89]
	v_mfma_f32_16x16x32_bf16 v[82:85], v[182:185], v[206:209], v[82:85]
	v_mfma_f32_16x16x32_bf16 v[70:73], v[174:177], v[214:217], v[70:73]
	v_mfma_f32_16x16x32_bf16 v[66:69], v[182:185], v[214:217], v[66:69]
	v_mfma_f32_16x16x32_bf16 v[118:121], v[178:181], v[194:197], v[118:121]
	v_mfma_f32_16x16x32_bf16 v[114:117], v[186:189], v[194:197], v[114:117]
	v_mfma_f32_16x16x32_bf16 v[102:105], v[178:181], v[202:205], v[102:105]
	v_mfma_f32_16x16x32_bf16 v[98:101], v[186:189], v[202:205], v[98:101]
	v_mfma_f32_16x16x32_bf16 v[86:89], v[178:181], v[210:213], v[86:89]
	v_mfma_f32_16x16x32_bf16 v[82:85], v[186:189], v[210:213], v[82:85]
	v_mfma_f32_16x16x32_bf16 v[70:73], v[178:181], v[224:227], v[70:73]
	v_mfma_f32_16x16x32_bf16 v[66:69], v[186:189], v[224:227], v[66:69]
	s_barrier
; #define PG8_STAGE(bufoff, gbase, voff) do { _Pragma("unroll") for (int _i = 0; _i < 2; ++_i) \
;         __builtin_amdgcn_global_load_lds((const unsigned*)((const char*)(gbase) + (voff)[_i]), (PG8_LAS unsigned*)(lds + (bufoff) + ldsw + _i * 8192), 16, 0, 0); } while (0)
; #define PG8_LDA(dst, b, h) do { _Pragma("unroll") for (int m = 0; m < 4; ++m) _Pragma("unroll") for (int k = 0; k < 2; ++k) dst[m][k] = *(const PG8_LAS bf16x8*)(lds + PG8_SA(b, h) + aoff + m * 2048 + k * 1024); } while (0)
; #define PG8_MMA(ai, bj, At, Bt) do { __builtin_amdgcn_s_setprio(1); _Pragma("unroll") for (int m = 0; m < 4; ++m) _Pragma("unroll") for (int n = 0; n < 2; ++n) _Pragma("unroll") for (int k = 0; k < 2; ++k) \
;         acc[ai][bj][m][n] = __builtin_amdgcn_mfma_f32_16x16x32_bf16(Bt[n][k], At[m][k], acc[ai][bj][m][n], 0, 0, 0); __builtin_amdgcn_s_setprio(0); } while (0)
; #define PG8_WAIT_V(n) asm volatile("s_waitcnt vmcnt(" #n ")" ::: "memory")
; #define PG8_WAIT_L(n) asm volatile("s_waitcnt lgkmcnt(" #n ")" ::: "memory")
; #define PG8_BAR __builtin_amdgcn_s_barrier()
; #define PG8_SCHED __builtin_amdgcn_sched_barrier(0)
; template <class Epi, class Sched, bool ALIGN_EPI = false, bool SP2 = false>
; __device__ __forceinline__ void gemm_phase(PG8_LAS unsigned char* lds, const Gemm g, const Sched& S, const Epi& E) {
;     ...
;             PG8_LDA(At, 1, 1); PG8_STAGE(PG8_SB(1, 0), b3, voffB); PG8_STAGE(PG8_SB(1, 1), b3 + hstep, voffB); PG8_STAGE(PG8_SA(1, 0), a3, voffA);
;             PG8_WAIT_V(8); PG8_WAIT_L(0); PG8_BAR; PG8_MMA(1, 0, At, B0); PG8_MMA(1, 1, At, B1); PG8_BAR; PG8_SCHED;
;     ...
;         if constexpr (ALIGN_EPI) { if (wr == 0) PG8_BAR; }
	s_add_i32 s30, s48, s12
	v_lshl_add_u64 v[160:161], v[160:161], 0, s[64:65]
	s_mov_b32 m0, s30
	ds_read_b128 v[190:193], v165 offset:49152
	ds_read_b128 v[194:197], v165 offset:50176
	ds_read_b128 v[198:201], v165 offset:51200
	ds_read_b128 v[202:205], v165 offset:52224
	ds_read_b128 v[206:209], v165 offset:53248
	ds_read_b128 v[210:213], v165 offset:54272
	ds_read_b128 v[214:217], v165 offset:55296
	ds_read_b128 v[224:227], v165 offset:56320
	global_load_lds_dwordx4 v[160:161], off
	s_add_i32 m0, s30, 0x2000
	s_add_u32 s28, s28, 0x80080
	v_lshl_add_u64 v[160:161], v[218:219], 0, s[64:65]
	s_addc_u32 s29, s29, 0
	s_add_i32 s30, s91, s12
	global_load_lds_dwordx4 v[160:161], off
	s_mov_b32 m0, s30
	s_nop 0
	global_load_lds_dwordx4 v0, s[28:29]
	s_add_i32 m0, s30, 0x2000
	s_nop 0
	global_load_lds_dwordx4 v126, s[28:29]
	s_mov_b32 m0, s43
	v_lshl_add_u64 v[160:161], v[220:221], 0, s[64:65]
	global_load_lds_dwordx4 v[160:161], off
	s_mov_b32 m0, s76
	v_lshl_add_u64 v[160:161], v[222:223], 0, s[64:65]
	global_load_lds_dwordx4 v[160:161], off
	s_waitcnt vmcnt(8) lgkmcnt(0)
	s_barrier
	v_mfma_f32_16x16x32_bf16 v[62:65], v[152:155], v[190:193], v[62:65]
	v_mfma_f32_16x16x32_bf16 v[58:61], v[166:169], v[190:193], v[58:61]
	v_mfma_f32_16x16x32_bf16 v[46:49], v[152:155], v[198:201], v[46:49]
	v_mfma_f32_16x16x32_bf16 v[42:45], v[166:169], v[198:201], v[42:45]
	v_mfma_f32_16x16x32_bf16 v[30:33], v[152:155], v[206:209], v[30:33]
	v_mfma_f32_16x16x32_bf16 v[26:29], v[166:169], v[206:209], v[26:29]
	v_mfma_f32_16x16x32_bf16 v[14:17], v[152:155], v[214:217], v[14:17]
	v_mfma_f32_16x16x32_bf16 v[10:13], v[166:169], v[214:217], v[10:13]
	v_mfma_f32_16x16x32_bf16 v[62:65], v[156:159], v[194:197], v[62:65]
	v_mfma_f32_16x16x32_bf16 v[58:61], v[170:173], v[194:197], v[58:61]
	v_mfma_f32_16x16x32_bf16 v[46:49], v[156:159], v[202:205], v[46:49]
	v_mfma_f32_16x16x32_bf16 v[42:45], v[170:173], v[202:205], v[42:45]
	v_mfma_f32_16x16x32_bf16 v[30:33], v[156:159], v[210:213], v[30:33]
	v_mfma_f32_16x16x32_bf16 v[26:29], v[170:173], v[210:213], v[26:29]
	v_mfma_f32_16x16x32_bf16 v[14:17], v[156:159], v[224:227], v[14:17]
	v_mfma_f32_16x16x32_bf16 v[10:13], v[170:173], v[224:227], v[10:13]
	v_mfma_f32_16x16x32_bf16 v[54:57], v[174:177], v[190:193], v[54:57]
	v_mfma_f32_16x16x32_bf16 v[50:53], v[182:185], v[190:193], v[50:53]
	v_mfma_f32_16x16x32_bf16 v[38:41], v[174:177], v[198:201], v[38:41]
	v_mfma_f32_16x16x32_bf16 v[34:37], v[182:185], v[198:201], v[34:37]
	v_mfma_f32_16x16x32_bf16 v[22:25], v[174:177], v[206:209], v[22:25]
	v_mfma_f32_16x16x32_bf16 v[18:21], v[182:185], v[206:209], v[18:21]
	v_mfma_f32_16x16x32_bf16 v[6:9], v[174:177], v[214:217], v[6:9]
	v_mfma_f32_16x16x32_bf16 v[2:5], v[182:185], v[214:217], v[2:5]
	v_mfma_f32_16x16x32_bf16 v[54:57], v[178:181], v[194:197], v[54:57]
	v_mfma_f32_16x16x32_bf16 v[50:53], v[186:189], v[194:197], v[50:53]
	v_mfma_f32_16x16x32_bf16 v[38:41], v[178:181], v[202:205], v[38:41]
	v_mfma_f32_16x16x32_bf16 v[34:37], v[186:189], v[202:205], v[34:37]
	v_mfma_f32_16x16x32_bf16 v[22:25], v[178:181], v[210:213], v[22:25]
	v_mfma_f32_16x16x32_bf16 v[18:21], v[186:189], v[210:213], v[18:21]
	v_mfma_f32_16x16x32_bf16 v[6:9], v[178:181], v[224:227], v[6:9]
	v_mfma_f32_16x16x32_bf16 v[2:5], v[186:189], v[224:227], v[2:5]
	s_barrier
	s_add_i32 s87, s87, 2
	s_add_u32 s8, s8, 0x100
	s_addc_u32 s9, s9, 0
	s_add_u32 s83, s83, 0x100
	s_addc_u32 s86, s86, 0
	s_cmp_gt_u32 s87, 29
	s_cbranch_scc0 .LBB0_808
	s_and_b64 vcc, exec, s[18:19]
	s_cbranch_vccz .LBB0_811
	s_barrier

; #define PG8_STAGE(bufoff, gbase, voff) do { _Pragma("unroll") for (int _i = 0; _i < 2; ++_i) \
;         __builtin_amdgcn_global_load_lds((const unsigned*)((const char*)(gbase) + (voff)[_i]), (PG8_LAS unsigned*)(lds + (bufoff) + ldsw + _i * 8192), 16, 0, 0); } while (0)
; #define PG8_LDA(dst, b, h) do { _Pragma("unroll") for (int m = 0; m < 4; ++m) _Pragma("unroll") for (int k = 0; k < 2; ++k) dst[m][k] = *(const PG8_LAS bf16x8*)(lds + PG8_SA(b, h) + aoff + m * 2048 + k * 1024); } while (0)
; #define PG8_LDB(dst, b, h) do { _Pragma("unroll") for (int n = 0; n < 2; ++n) _Pragma("unroll") for (int k = 0; k < 2; ++k) dst[n][k] = *(const PG8_LAS bf16x8*)(lds + PG8_SB(b, h) + boff + n * 2048 + k * 1024); } while (0)
; #define PG8_MMA(ai, bj, At, Bt) do { __builtin_amdgcn_s_setprio(1); _Pragma("unroll") for (int m = 0; m < 4; ++m) _Pragma("unroll") for (int n = 0; n < 2; ++n) _Pragma("unroll") for (int k = 0; k < 2; ++k) \
;         acc[ai][bj][m][n] = __builtin_amdgcn_mfma_f32_16x16x32_bf16(Bt[n][k], At[m][k], acc[ai][bj][m][n], 0, 0, 0); __builtin_amdgcn_s_setprio(0); } while (0)
; #define PG8_WAIT_V(n) asm volatile("s_waitcnt vmcnt(" #n ")" ::: "memory")
; #define PG8_WAIT_L(n) asm volatile("s_waitcnt lgkmcnt(" #n ")" ::: "memory")
; #define PG8_BAR __builtin_amdgcn_s_barrier()
; #define PG8_SCHED __builtin_amdgcn_sched_barrier(0)
; template <class Epi, class Sched, bool ALIGN_EPI = false, bool SP2 = false>
; __device__ __forceinline__ void gemm_phase(PG8_LAS unsigned char* lds, const Gemm g, const Sched& S, const Epi& E) {
;     ...
;             PG8_LDB(B0, 0, 0); PG8_LDB(B1, 0, 1); PG8_SCHED; PG8_LDA(At, 0, 0); PG8_STAGE(PG8_SA(1, 1), a1 + hstep, voffA);
;             PG8_WAIT_V(8); PG8_WAIT_L(0); PG8_BAR; PG8_MMA(0, 0, At, B0); PG8_MMA(0, 1, At, B1); PG8_BAR; PG8_SCHED;
;             PG8_LDA(At, 0, 1); PG8_STAGE(PG8_SB(0, 0), b2, voffB); PG8_STAGE(PG8_SB(0, 1), b2 + hstep, voffB); PG8_STAGE(PG8_SA(0, 0), a2, voffA);
;             PG8_WAIT_V(8); PG8_WAIT_L(0); PG8_BAR; PG8_MMA(1, 0, At, B0); PG8_MMA(1, 1, At, B1); PG8_BAR; PG8_SCHED;
.LBB0_910:
	s_add_u32 s28, s0, 0xfff80080
	s_addc_u32 s29, s1, -1
	s_add_i32 s48, 0, 0x10000
	s_cmp_eq_u32 s81, 28
	s_cselect_b32 s31, s21, s29
	s_cselect_b32 s30, s35, s28
	s_cselect_b32 s29, s23, s67
	s_cselect_b32 s28, s40, s41
	s_add_i32 s91, 0, 0x14000
	v_add_u32_e32 v164, s48, v179
	v_add_u32_e32 v176, s91, v179
	ds_read_b128 v[152:155], v164
	ds_read_b128 v[156:159], v164 offset:1024
	ds_read_b128 v[160:163], v164 offset:2048
	ds_read_b128 v[164:167], v164 offset:3072
	ds_read_b128 v[168:171], v176
	ds_read_b128 v[172:175], v176 offset:1024
	ds_read_b128 v[182:185], v176 offset:2048
	ds_read_b128 v[186:189], v176 offset:3072
	s_add_i32 m0, s43, 0xc000
	ds_read_b128 v[190:193], v181
	ds_read_b128 v[194:197], v181 offset:1024
	ds_read_b128 v[198:201], v181 offset:2048
	ds_read_b128 v[202:205], v181 offset:3072
	ds_read_b128 v[206:209], v181 offset:4096
	ds_read_b128 v[210:213], v181 offset:5120
	ds_read_b128 v[214:217], v181 offset:6144
	ds_read_b128 v[224:227], v181 offset:7168
	global_load_lds_dwordx4 v148, s[0:1]
	s_add_i32 m0, s43, 0xe000
	s_nop 0
	global_load_lds_dwordx4 v150, s[0:1]
	s_waitcnt vmcnt(8) lgkmcnt(0)
	s_barrier
	v_mfma_f32_16x16x32_bf16 v[74:77], v[152:155], v[190:193], v[74:77]
	v_mfma_f32_16x16x32_bf16 v[78:81], v[160:163], v[190:193], v[78:81]
	v_mfma_f32_16x16x32_bf16 v[102:105], v[152:155], v[198:201], v[102:105]
	v_mfma_f32_16x16x32_bf16 v[106:109], v[160:163], v[198:201], v[106:109]
	v_mfma_f32_16x16x32_bf16 v[122:125], v[152:155], v[206:209], v[122:125]
	v_mfma_f32_16x16x32_bf16 v[144:147], v[160:163], v[206:209], v[144:147]
	v_mfma_f32_16x16x32_bf16 v[90:93], v[152:155], v[214:217], v[90:93]
	v_mfma_f32_16x16x32_bf16 v[86:89], v[160:163], v[214:217], v[86:89]
	v_mfma_f32_16x16x32_bf16 v[74:77], v[156:159], v[194:197], v[74:77]
	v_mfma_f32_16x16x32_bf16 v[78:81], v[164:167], v[194:197], v[78:81]
	v_mfma_f32_16x16x32_bf16 v[102:105], v[156:159], v[202:205], v[102:105]
	v_mfma_f32_16x16x32_bf16 v[106:109], v[164:167], v[202:205], v[106:109]
	v_mfma_f32_16x16x32_bf16 v[122:125], v[156:159], v[210:213], v[122:125]
	v_mfma_f32_16x16x32_bf16 v[144:147], v[164:167], v[210:213], v[144:147]
	v_mfma_f32_16x16x32_bf16 v[90:93], v[156:159], v[224:227], v[90:93]
	v_mfma_f32_16x16x32_bf16 v[86:89], v[164:167], v[224:227], v[86:89]
	v_mfma_f32_16x16x32_bf16 v[82:85], v[168:171], v[190:193], v[82:85]
	v_mfma_f32_16x16x32_bf16 v[94:97], v[182:185], v[190:193], v[94:97]
	v_mfma_f32_16x16x32_bf16 v[110:113], v[168:171], v[198:201], v[110:113]
	v_mfma_f32_16x16x32_bf16 v[118:121], v[182:185], v[198:201], v[118:121]
	v_mfma_f32_16x16x32_bf16 v[114:117], v[168:171], v[206:209], v[114:117]
	v_mfma_f32_16x16x32_bf16 v[98:101], v[182:185], v[206:209], v[98:101]
	v_mfma_f32_16x16x32_bf16 v[70:73], v[168:171], v[214:217], v[70:73]
	v_mfma_f32_16x16x32_bf16 v[66:69], v[182:185], v[214:217], v[66:69]
	v_mfma_f32_16x16x32_bf16 v[82:85], v[172:175], v[194:197], v[82:85]
	v_mfma_f32_16x16x32_bf16 v[94:97], v[186:189], v[194:197], v[94:97]
	v_mfma_f32_16x16x32_bf16 v[110:113], v[172:175], v[202:205], v[110:113]
	v_mfma_f32_16x16x32_bf16 v[118:121], v[186:189], v[202:205], v[118:121]
	v_mfma_f32_16x16x32_bf16 v[114:117], v[172:175], v[210:213], v[114:117]
	v_mfma_f32_16x16x32_bf16 v[98:101], v[186:189], v[210:213], v[98:101]
	v_mfma_f32_16x16x32_bf16 v[70:73], v[172:175], v[224:227], v[70:73]
	v_mfma_f32_16x16x32_bf16 v[66:69], v[186:189], v[224:227], v[66:69]
	s_barrier
	s_add_i32 s48, s48, s42
	v_lshl_add_u64 v[176:177], s[28:29], 0, v[0:1]
	s_mov_b32 m0, s48
	ds_read_b128 v[190:193], v181 offset:16384
	ds_read_b128 v[194:197], v181 offset:17408
	ds_read_b128 v[198:201], v181 offset:18432
	ds_read_b128 v[202:205], v181 offset:19456
	ds_read_b128 v[206:209], v181 offset:20480
	ds_read_b128 v[210:213], v181 offset:21504
	ds_read_b128 v[214:217], v181 offset:22528
	ds_read_b128 v[224:227], v181 offset:23552
	global_load_lds_dwordx4 v[176:177], off
	s_add_i32 m0, s48, 0x2000
	s_add_u32 vcc_lo, s28, 0x80000
	v_lshl_add_u64 v[218:219], s[28:29], 0, v[126:127]
	s_addc_u32 vcc_hi, s29, 0
	s_add_i32 s48, s91, s42
	global_load_lds_dwordx4 v[218:219], off
	v_lshl_add_u64 v[220:221], vcc, 0, v[0:1]
	s_mov_b32 m0, s48
	v_lshl_add_u64 v[222:223], s[30:31], 0, v[126:127]
	global_load_lds_dwordx4 v[220:221], off
	s_add_i32 m0, s48, 0x2000
	v_lshl_add_u64 v[220:221], vcc, 0, v[126:127]
	global_load_lds_dwordx4 v[220:221], off
	s_mov_b32 m0, s43
	v_lshl_add_u64 v[220:221], s[30:31], 0, v[0:1]
	global_load_lds_dwordx4 v[220:221], off
	s_mov_b32 m0, s76
	s_nop 0
	global_load_lds_dwordx4 v[222:223], off
	s_waitcnt vmcnt(8) lgkmcnt(0)
	s_barrier
; #define PG8_STAGE(bufoff, gbase, voff) do { _Pragma("unroll") for (int _i = 0; _i < 2; ++_i) \
;         __builtin_amdgcn_global_load_lds((const unsigned*)((const char*)(gbase) + (voff)[_i]), (PG8_LAS unsigned*)(lds + (bufoff) + ldsw + _i * 8192), 16, 0, 0); } while (0)
; #define PG8_LDA(dst, b, h) do { _Pragma("unroll") for (int m = 0; m < 4; ++m) _Pragma("unroll") for (int k = 0; k < 2; ++k) dst[m][k] = *(const PG8_LAS bf16x8*)(lds + PG8_SA(b, h) + aoff + m * 2048 + k * 1024); } while (0)
; #define PG8_LDB(dst, b, h) do { _Pragma("unroll") for (int n = 0; n < 2; ++n) _Pragma("unroll") for (int k = 0; k < 2; ++k) dst[n][k] = *(const PG8_LAS bf16x8*)(lds + PG8_SB(b, h) + boff + n * 2048 + k * 1024); } while (0)
; #define PG8_MMA(ai, bj, At, Bt) do { __builtin_amdgcn_s_setprio(1); _Pragma("unroll") for (int m = 0; m < 4; ++m) _Pragma("unroll") for (int n = 0; n < 2; ++n) _Pragma("unroll") for (int k = 0; k < 2; ++k) \
;         acc[ai][bj][m][n] = __builtin_amdgcn_mfma_f32_16x16x32_bf16(Bt[n][k], At[m][k], acc[ai][bj][m][n], 0, 0, 0); __builtin_amdgcn_s_setprio(0); } while (0)
; #define PG8_WAIT_V(n) asm volatile("s_waitcnt vmcnt(" #n ")" ::: "memory")
; #define PG8_WAIT_L(n) asm volatile("s_waitcnt lgkmcnt(" #n ")" ::: "memory")
; #define PG8_BAR __builtin_amdgcn_s_barrier()
; #define PG8_SCHED __builtin_amdgcn_sched_barrier(0)
; template <class Epi, class Sched, bool ALIGN_EPI = false, bool SP2 = false>
; __device__ __forceinline__ void gemm_phase(PG8_LAS unsigned char* lds, const Gemm g, const Sched& S, const Epi& E) {
;     ...
;             PG8_WAIT_V(8); PG8_WAIT_L(0); PG8_BAR; PG8_MMA(1, 0, At, B0); PG8_MMA(1, 1, At, B1); PG8_BAR; PG8_SCHED;
;             PG8_LDB(B0, 1, 0); PG8_LDB(B1, 1, 1); PG8_SCHED; PG8_LDA(At, 1, 0); PG8_STAGE(PG8_SA(0, 1), a2 + hstep, voffA);
;             PG8_WAIT_V(8); PG8_WAIT_L(0); PG8_BAR; PG8_MMA(0, 0, At, B0); PG8_MMA(0, 1, At, B1); PG8_BAR; PG8_SCHED;
	v_mfma_f32_16x16x32_bf16 v[62:65], v[152:155], v[190:193], v[62:65]
	v_mfma_f32_16x16x32_bf16 v[58:61], v[160:163], v[190:193], v[58:61]
	v_mfma_f32_16x16x32_bf16 v[46:49], v[152:155], v[198:201], v[46:49]
	v_mfma_f32_16x16x32_bf16 v[42:45], v[160:163], v[198:201], v[42:45]
	v_mfma_f32_16x16x32_bf16 v[30:33], v[152:155], v[206:209], v[30:33]
	v_mfma_f32_16x16x32_bf16 v[26:29], v[160:163], v[206:209], v[26:29]
	v_mfma_f32_16x16x32_bf16 v[14:17], v[152:155], v[214:217], v[14:17]
	v_mfma_f32_16x16x32_bf16 v[10:13], v[160:163], v[214:217], v[10:13]
	v_mfma_f32_16x16x32_bf16 v[62:65], v[156:159], v[194:197], v[62:65]
	v_mfma_f32_16x16x32_bf16 v[58:61], v[164:167], v[194:197], v[58:61]
	v_mfma_f32_16x16x32_bf16 v[46:49], v[156:159], v[202:205], v[46:49]
	v_mfma_f32_16x16x32_bf16 v[42:45], v[164:167], v[202:205], v[42:45]
	v_mfma_f32_16x16x32_bf16 v[30:33], v[156:159], v[210:213], v[30:33]
	v_mfma_f32_16x16x32_bf16 v[26:29], v[164:167], v[210:213], v[26:29]
	v_mfma_f32_16x16x32_bf16 v[14:17], v[156:159], v[224:227], v[14:17]
	v_mfma_f32_16x16x32_bf16 v[10:13], v[164:167], v[224:227], v[10:13]
	v_mfma_f32_16x16x32_bf16 v[54:57], v[168:171], v[190:193], v[54:57]
	v_mfma_f32_16x16x32_bf16 v[50:53], v[182:185], v[190:193], v[50:53]
	v_mfma_f32_16x16x32_bf16 v[38:41], v[168:171], v[198:201], v[38:41]
	v_mfma_f32_16x16x32_bf16 v[34:37], v[182:185], v[198:201], v[34:37]
	v_mfma_f32_16x16x32_bf16 v[22:25], v[168:171], v[206:209], v[22:25]
	v_mfma_f32_16x16x32_bf16 v[18:21], v[182:185], v[206:209], v[18:21]
	v_mfma_f32_16x16x32_bf16 v[6:9], v[168:171], v[214:217], v[6:9]
	v_mfma_f32_16x16x32_bf16 v[2:5], v[182:185], v[214:217], v[2:5]
	v_mfma_f32_16x16x32_bf16 v[54:57], v[172:175], v[194:197], v[54:57]
	v_mfma_f32_16x16x32_bf16 v[50:53], v[186:189], v[194:197], v[50:53]
	v_mfma_f32_16x16x32_bf16 v[38:41], v[172:175], v[202:205], v[38:41]
	v_mfma_f32_16x16x32_bf16 v[34:37], v[186:189], v[202:205], v[34:37]
	v_mfma_f32_16x16x32_bf16 v[22:25], v[172:175], v[210:213], v[22:25]
	v_mfma_f32_16x16x32_bf16 v[18:21], v[186:189], v[210:213], v[18:21]
	v_mfma_f32_16x16x32_bf16 v[6:9], v[172:175], v[224:227], v[6:9]
	v_mfma_f32_16x16x32_bf16 v[2:5], v[186:189], v[224:227], v[2:5]
	s_barrier
	s_add_i32 s48, 0, 0x18000
	s_add_i32 s91, 0, 0x1c000
	v_add_u32_e32 v164, s48, v179
	v_add_u32_e32 v186, s91, v179
	ds_read_b128 v[152:155], v164
	ds_read_b128 v[156:159], v164 offset:1024
	ds_read_b128 v[160:163], v164 offset:2048
	ds_read_b128 v[164:167], v164 offset:3072
	ds_read_b128 v[168:171], v186
	ds_read_b128 v[172:175], v186 offset:1024
	ds_read_b128 v[182:185], v186 offset:2048
	ds_read_b128 v[186:189], v186 offset:3072
	s_add_u32 s30, s30, 0x80000
	s_addc_u32 s31, s31, 0
	s_mov_b32 m0, s82
	ds_read_b128 v[190:193], v181 offset:32768
	ds_read_b128 v[194:197], v181 offset:33792
	ds_read_b128 v[198:201], v181 offset:34816
	ds_read_b128 v[202:205], v181 offset:35840
	ds_read_b128 v[206:209], v181 offset:36864
	ds_read_b128 v[210:213], v181 offset:37888
	ds_read_b128 v[214:217], v181 offset:38912
	ds_read_b128 v[224:227], v181 offset:39936
	global_load_lds_dwordx4 v0, s[30:31]
	s_mov_b32 m0, s83
	s_nop 0
	global_load_lds_dwordx4 v126, s[30:31]
	s_waitcnt vmcnt(8) lgkmcnt(0)
	s_barrier
	v_mfma_f32_16x16x32_bf16 v[74:77], v[152:155], v[190:193], v[74:77]
	v_mfma_f32_16x16x32_bf16 v[78:81], v[160:163], v[190:193], v[78:81]
	v_mfma_f32_16x16x32_bf16 v[102:105], v[152:155], v[198:201], v[102:105]
	v_mfma_f32_16x16x32_bf16 v[106:109], v[160:163], v[198:201], v[106:109]
	v_mfma_f32_16x16x32_bf16 v[122:125], v[152:155], v[206:209], v[122:125]
	v_mfma_f32_16x16x32_bf16 v[144:147], v[160:163], v[206:209], v[144:147]
	v_mfma_f32_16x16x32_bf16 v[90:93], v[152:155], v[214:217], v[90:93]
	v_mfma_f32_16x16x32_bf16 v[86:89], v[160:163], v[214:217], v[86:89]
	v_mfma_f32_16x16x32_bf16 v[74:77], v[156:159], v[194:197], v[74:77]
	v_mfma_f32_16x16x32_bf16 v[78:81], v[164:167], v[194:197], v[78:81]
	v_mfma_f32_16x16x32_bf16 v[102:105], v[156:159], v[202:205], v[102:105]
	v_mfma_f32_16x16x32_bf16 v[106:109], v[164:167], v[202:205], v[106:109]
	v_mfma_f32_16x16x32_bf16 v[122:125], v[156:159], v[210:213], v[122:125]
	v_mfma_f32_16x16x32_bf16 v[144:147], v[164:167], v[210:213], v[144:147]
	v_mfma_f32_16x16x32_bf16 v[90:93], v[156:159], v[224:227], v[90:93]
	v_mfma_f32_16x16x32_bf16 v[86:89], v[164:167], v[224:227], v[86:89]
	v_mfma_f32_16x16x32_bf16 v[82:85], v[168:171], v[190:193], v[82:85]
	v_mfma_f32_16x16x32_bf16 v[94:97], v[182:185], v[190:193], v[94:97]
	v_mfma_f32_16x16x32_bf16 v[110:113], v[168:171], v[198:201], v[110:113]
	v_mfma_f32_16x16x32_bf16 v[118:121], v[182:185], v[198:201], v[118:121]
	v_mfma_f32_16x16x32_bf16 v[114:117], v[168:171], v[206:209], v[114:117]
	v_mfma_f32_16x16x32_bf16 v[98:101], v[182:185], v[206:209], v[98:101]
	v_mfma_f32_16x16x32_bf16 v[70:73], v[168:171], v[214:217], v[70:73]
	v_mfma_f32_16x16x32_bf16 v[66:69], v[182:185], v[214:217], v[66:69]
	v_mfma_f32_16x16x32_bf16 v[82:85], v[172:175], v[194:197], v[82:85]
	v_mfma_f32_16x16x32_bf16 v[94:97], v[186:189], v[194:197], v[94:97]
	v_mfma_f32_16x16x32_bf16 v[110:113], v[172:175], v[202:205], v[110:113]
	v_mfma_f32_16x16x32_bf16 v[118:121], v[186:189], v[202:205], v[118:121]
	v_mfma_f32_16x16x32_bf16 v[114:117], v[172:175], v[210:213], v[114:117]
	v_mfma_f32_16x16x32_bf16 v[98:101], v[186:189], v[210:213], v[98:101]
	v_mfma_f32_16x16x32_bf16 v[70:73], v[172:175], v[224:227], v[70:73]
	v_mfma_f32_16x16x32_bf16 v[66:69], v[186:189], v[224:227], v[66:69]
	s_barrier
; #define PG8_STAGE(bufoff, gbase, voff) do { _Pragma("unroll") for (int _i = 0; _i < 2; ++_i) \
;         __builtin_amdgcn_global_load_lds((const unsigned*)((const char*)(gbase) + (voff)[_i]), (PG8_LAS unsigned*)(lds + (bufoff) + ldsw + _i * 8192), 16, 0, 0); } while (0)
; #define PG8_LDA(dst, b, h) do { _Pragma("unroll") for (int m = 0; m < 4; ++m) _Pragma("unroll") for (int k = 0; k < 2; ++k) dst[m][k] = *(const PG8_LAS bf16x8*)(lds + PG8_SA(b, h) + aoff + m * 2048 + k * 1024); } while (0)
; #define PG8_MMA(ai, bj, At, Bt) do { __builtin_amdgcn_s_setprio(1); _Pragma("unroll") for (int m = 0; m < 4; ++m) _Pragma("unroll") for (int n = 0; n < 2; ++n) _Pragma("unroll") for (int k = 0; k < 2; ++k) \
;         acc[ai][bj][m][n] = __builtin_amdgcn_mfma_f32_16x16x32_bf16(Bt[n][k], At[m][k], acc[ai][bj][m][n], 0, 0, 0); __builtin_amdgcn_s_setprio(0); } while (0)
; #define PG8_WAIT_V(n) asm volatile("s_waitcnt vmcnt(" #n ")" ::: "memory")
; #define PG8_WAIT_L(n) asm volatile("s_waitcnt lgkmcnt(" #n ")" ::: "memory")
; #define PG8_BAR __builtin_amdgcn_s_barrier()
; #define PG8_SCHED __builtin_amdgcn_sched_barrier(0)
; template <class Epi, class Sched, bool ALIGN_EPI = false, bool SP2 = false>
; __device__ __forceinline__ void gemm_phase(PG8_LAS unsigned char* lds, const Gemm g, const Sched& S, const Epi& E) {
;     ...
;             PG8_LDA(At, 1, 1); PG8_STAGE(PG8_SB(1, 0), b3, voffB); PG8_STAGE(PG8_SB(1, 1), b3 + hstep, voffB); PG8_STAGE(PG8_SA(1, 0), a3, voffA);
;             PG8_WAIT_V(8); PG8_WAIT_L(0); PG8_BAR; PG8_MMA(1, 0, At, B0); PG8_MMA(1, 1, At, B1); PG8_BAR; PG8_SCHED;
;     ...
;         if constexpr (ALIGN_EPI) { if (wr == 0) PG8_BAR; }
	s_add_i32 s30, s48, s42
	v_lshl_add_u64 v[176:177], v[176:177], 0, s[64:65]
	s_mov_b32 m0, s30
	ds_read_b128 v[190:193], v181 offset:49152
	ds_read_b128 v[194:197], v181 offset:50176
	ds_read_b128 v[198:201], v181 offset:51200
	ds_read_b128 v[202:205], v181 offset:52224
	ds_read_b128 v[206:209], v181 offset:53248
	ds_read_b128 v[210:213], v181 offset:54272
	ds_read_b128 v[214:217], v181 offset:55296
	ds_read_b128 v[224:227], v181 offset:56320
	global_load_lds_dwordx4 v[176:177], off
	s_add_i32 m0, s30, 0x2000
	s_add_u32 s28, s28, 0x80080
	v_lshl_add_u64 v[176:177], v[218:219], 0, s[64:65]
	s_addc_u32 s29, s29, 0
	s_add_i32 s30, s91, s42
	global_load_lds_dwordx4 v[176:177], off
	s_mov_b32 m0, s30
	s_nop 0
	global_load_lds_dwordx4 v0, s[28:29]
	s_add_i32 m0, s30, 0x2000
	s_nop 0
	global_load_lds_dwordx4 v126, s[28:29]
	s_mov_b32 m0, s86
	v_lshl_add_u64 v[176:177], v[220:221], 0, s[64:65]
	global_load_lds_dwordx4 v[176:177], off
	s_mov_b32 m0, s87
	v_lshl_add_u64 v[176:177], v[222:223], 0, s[64:65]
	global_load_lds_dwordx4 v[176:177], off
	s_waitcnt vmcnt(8) lgkmcnt(0)
	s_barrier
	v_mfma_f32_16x16x32_bf16 v[62:65], v[152:155], v[190:193], v[62:65]
	v_mfma_f32_16x16x32_bf16 v[58:61], v[160:163], v[190:193], v[58:61]
	v_mfma_f32_16x16x32_bf16 v[46:49], v[152:155], v[198:201], v[46:49]
	v_mfma_f32_16x16x32_bf16 v[42:45], v[160:163], v[198:201], v[42:45]
	v_mfma_f32_16x16x32_bf16 v[30:33], v[152:155], v[206:209], v[30:33]
	v_mfma_f32_16x16x32_bf16 v[26:29], v[160:163], v[206:209], v[26:29]
	v_mfma_f32_16x16x32_bf16 v[14:17], v[152:155], v[214:217], v[14:17]
	v_mfma_f32_16x16x32_bf16 v[10:13], v[160:163], v[214:217], v[10:13]
	v_mfma_f32_16x16x32_bf16 v[62:65], v[156:159], v[194:197], v[62:65]
	v_mfma_f32_16x16x32_bf16 v[58:61], v[164:167], v[194:197], v[58:61]
	v_mfma_f32_16x16x32_bf16 v[46:49], v[156:159], v[202:205], v[46:49]
	v_mfma_f32_16x16x32_bf16 v[42:45], v[164:167], v[202:205], v[42:45]
	v_mfma_f32_16x16x32_bf16 v[30:33], v[156:159], v[210:213], v[30:33]
	v_mfma_f32_16x16x32_bf16 v[26:29], v[164:167], v[210:213], v[26:29]
	v_mfma_f32_16x16x32_bf16 v[14:17], v[156:159], v[224:227], v[14:17]
	v_mfma_f32_16x16x32_bf16 v[10:13], v[164:167], v[224:227], v[10:13]
	v_mfma_f32_16x16x32_bf16 v[54:57], v[168:171], v[190:193], v[54:57]
	v_mfma_f32_16x16x32_bf16 v[50:53], v[182:185], v[190:193], v[50:53]
	v_mfma_f32_16x16x32_bf16 v[38:41], v[168:171], v[198:201], v[38:41]
	v_mfma_f32_16x16x32_bf16 v[34:37], v[182:185], v[198:201], v[34:37]
	v_mfma_f32_16x16x32_bf16 v[22:25], v[168:171], v[206:209], v[22:25]
	v_mfma_f32_16x16x32_bf16 v[18:21], v[182:185], v[206:209], v[18:21]
	v_mfma_f32_16x16x32_bf16 v[6:9], v[168:171], v[214:217], v[6:9]
	v_mfma_f32_16x16x32_bf16 v[2:5], v[182:185], v[214:217], v[2:5]
	v_mfma_f32_16x16x32_bf16 v[54:57], v[172:175], v[194:197], v[54:57]
	v_mfma_f32_16x16x32_bf16 v[50:53], v[186:189], v[194:197], v[50:53]
	v_mfma_f32_16x16x32_bf16 v[38:41], v[172:175], v[202:205], v[38:41]
	v_mfma_f32_16x16x32_bf16 v[34:37], v[186:189], v[202:205], v[34:37]
	v_mfma_f32_16x16x32_bf16 v[22:25], v[172:175], v[210:213], v[22:25]
	v_mfma_f32_16x16x32_bf16 v[18:21], v[186:189], v[210:213], v[18:21]
	v_mfma_f32_16x16x32_bf16 v[6:9], v[172:175], v[224:227], v[6:9]
	v_mfma_f32_16x16x32_bf16 v[2:5], v[186:189], v[224:227], v[2:5]
	s_barrier
	s_add_i32 s81, s81, 2
	s_add_u32 s0, s0, 0x100
	s_addc_u32 s1, s1, 0
	s_add_u32 s41, s41, 0x100
	s_addc_u32 s67, s67, 0
	s_cmp_gt_u32 s81, 29
	s_cbranch_scc0 .LBB0_910
	s_and_b64 vcc, exec, s[18:19]
	s_cbranch_vccz .LBB0_913
	s_barrier

; #define PG8_STAGE(bufoff, gbase, voff) do { _Pragma("unroll") for (int _i = 0; _i < 2; ++_i) \
;         __builtin_amdgcn_global_load_lds((const unsigned*)((const char*)(gbase) + (voff)[_i]), (PG8_LAS unsigned*)(lds + (bufoff) + ldsw + _i * 8192), 16, 0, 0); } while (0)
; #define PG8_LDA(dst, b, h) do { _Pragma("unroll") for (int m = 0; m < 4; ++m) _Pragma("unroll") for (int k = 0; k < 2; ++k) dst[m][k] = *(const PG8_LAS bf16x8*)(lds + PG8_SA(b, h) + aoff + m * 2048 + k * 1024); } while (0)
; #define PG8_LDB(dst, b, h) do { _Pragma("unroll") for (int n = 0; n < 2; ++n) _Pragma("unroll") for (int k = 0; k < 2; ++k) dst[n][k] = *(const PG8_LAS bf16x8*)(lds + PG8_SB(b, h) + boff + n * 2048 + k * 1024); } while (0)
; #define PG8_MMA(ai, bj, At, Bt) do { __builtin_amdgcn_s_setprio(1); _Pragma("unroll") for (int m = 0; m < 4; ++m) _Pragma("unroll") for (int n = 0; n < 2; ++n) _Pragma("unroll") for (int k = 0; k < 2; ++k) \
;         acc[ai][bj][m][n] = __builtin_amdgcn_mfma_f32_16x16x32_bf16(Bt[n][k], At[m][k], acc[ai][bj][m][n], 0, 0, 0); __builtin_amdgcn_s_setprio(0); } while (0)
; #define PG8_WAIT_V(n) asm volatile("s_waitcnt vmcnt(" #n ")" ::: "memory")
; #define PG8_WAIT_L(n) asm volatile("s_waitcnt lgkmcnt(" #n ")" ::: "memory")
; #define PG8_BAR __builtin_amdgcn_s_barrier()
; #define PG8_SCHED __builtin_amdgcn_sched_barrier(0)
; template <class Epi, class Sched, bool ALIGN_EPI = false, bool SP2 = false>
; __device__ __forceinline__ void gemm_phase(PG8_LAS unsigned char* lds, const Gemm g, const Sched& S, const Epi& E) {
;     ...
;             PG8_LDB(B0, 0, 0); PG8_LDB(B1, 0, 1); PG8_SCHED; PG8_LDA(At, 0, 0); PG8_STAGE(PG8_SA(1, 1), a1 + hstep, voffA);
;             PG8_WAIT_V(8); PG8_WAIT_L(0); PG8_BAR; PG8_MMA(0, 0, At, B0); PG8_MMA(0, 1, At, B1); PG8_BAR; PG8_SCHED;
;             PG8_LDA(At, 0, 1); PG8_STAGE(PG8_SB(0, 0), b2, voffB); PG8_STAGE(PG8_SB(0, 1), b2 + hstep, voffB); PG8_STAGE(PG8_SA(0, 0), a2, voffA);
;             PG8_WAIT_V(8); PG8_WAIT_L(0); PG8_BAR; PG8_MMA(1, 0, At, B0); PG8_MMA(1, 1, At, B1); PG8_BAR; PG8_SCHED;
.LBB0_963:
	s_add_u32 s24, s0, 0xfff80080
	s_addc_u32 s25, s1, -1
	s_add_i32 s43, 0, 0x10000
	s_cmp_eq_u32 s42, 28
	s_cselect_b32 s27, s13, s25
	s_cselect_b32 s26, s17, s24
	s_cselect_b32 s25, s19, s41
	s_cselect_b32 s24, s29, s40
	s_add_i32 s48, 0, 0x14000
	v_add_u32_e32 v164, s43, v197
	v_add_u32_e32 v180, s48, v197
	ds_read_b128 v[152:155], v164
	ds_read_b128 v[156:159], v164 offset:1024
	ds_read_b128 v[160:163], v164 offset:2048
	ds_read_b128 v[164:167], v164 offset:3072
	ds_read_b128 v[168:171], v180
	ds_read_b128 v[172:175], v180 offset:1024
	ds_read_b128 v[176:179], v180 offset:2048
	ds_read_b128 v[180:183], v180 offset:3072
	s_add_i32 m0, s31, 0xc000
	ds_read_b128 v[184:187], v199
	ds_read_b128 v[188:191], v199 offset:1024
	ds_read_b128 v[192:195], v199 offset:2048
	ds_read_b128 v[200:203], v199 offset:3072
	ds_read_b128 v[204:207], v199 offset:4096
	ds_read_b128 v[208:211], v199 offset:5120
	ds_read_b128 v[212:215], v199 offset:6144
	ds_read_b128 v[216:219], v199 offset:7168
	global_load_lds_dwordx4 v148, s[0:1]
	s_add_i32 m0, s31, 0xe000
	s_nop 0
	global_load_lds_dwordx4 v150, s[0:1]
	s_waitcnt vmcnt(8) lgkmcnt(0)
	s_barrier
	v_mfma_f32_16x16x32_bf16 v[144:147], v[152:155], v[184:187], v[144:147]
	v_mfma_f32_16x16x32_bf16 v[122:125], v[160:163], v[184:187], v[122:125]
	v_mfma_f32_16x16x32_bf16 v[110:113], v[152:155], v[192:195], v[110:113]
	v_mfma_f32_16x16x32_bf16 v[106:109], v[160:163], v[192:195], v[106:109]
	v_mfma_f32_16x16x32_bf16 v[94:97], v[152:155], v[204:207], v[94:97]
	v_mfma_f32_16x16x32_bf16 v[90:93], v[160:163], v[204:207], v[90:93]
	v_mfma_f32_16x16x32_bf16 v[78:81], v[152:155], v[212:215], v[78:81]
	v_mfma_f32_16x16x32_bf16 v[74:77], v[160:163], v[212:215], v[74:77]
	v_mfma_f32_16x16x32_bf16 v[144:147], v[156:159], v[188:191], v[144:147]
	v_mfma_f32_16x16x32_bf16 v[122:125], v[164:167], v[188:191], v[122:125]
	v_mfma_f32_16x16x32_bf16 v[110:113], v[156:159], v[200:203], v[110:113]
	v_mfma_f32_16x16x32_bf16 v[106:109], v[164:167], v[200:203], v[106:109]
	v_mfma_f32_16x16x32_bf16 v[94:97], v[156:159], v[208:211], v[94:97]
	v_mfma_f32_16x16x32_bf16 v[90:93], v[164:167], v[208:211], v[90:93]
	v_mfma_f32_16x16x32_bf16 v[78:81], v[156:159], v[216:219], v[78:81]
	v_mfma_f32_16x16x32_bf16 v[74:77], v[164:167], v[216:219], v[74:77]
	v_mfma_f32_16x16x32_bf16 v[118:121], v[168:171], v[184:187], v[118:121]
	v_mfma_f32_16x16x32_bf16 v[114:117], v[176:179], v[184:187], v[114:117]
	v_mfma_f32_16x16x32_bf16 v[102:105], v[168:171], v[192:195], v[102:105]
	v_mfma_f32_16x16x32_bf16 v[98:101], v[176:179], v[192:195], v[98:101]
	v_mfma_f32_16x16x32_bf16 v[86:89], v[168:171], v[204:207], v[86:89]
	v_mfma_f32_16x16x32_bf16 v[82:85], v[176:179], v[204:207], v[82:85]
	v_mfma_f32_16x16x32_bf16 v[70:73], v[168:171], v[212:215], v[70:73]
	v_mfma_f32_16x16x32_bf16 v[66:69], v[176:179], v[212:215], v[66:69]
	v_mfma_f32_16x16x32_bf16 v[118:121], v[172:175], v[188:191], v[118:121]
	v_mfma_f32_16x16x32_bf16 v[114:117], v[180:183], v[188:191], v[114:117]
	v_mfma_f32_16x16x32_bf16 v[102:105], v[172:175], v[200:203], v[102:105]
	v_mfma_f32_16x16x32_bf16 v[98:101], v[180:183], v[200:203], v[98:101]
	v_mfma_f32_16x16x32_bf16 v[86:89], v[172:175], v[208:211], v[86:89]
	v_mfma_f32_16x16x32_bf16 v[82:85], v[180:183], v[208:211], v[82:85]
	v_mfma_f32_16x16x32_bf16 v[70:73], v[172:175], v[216:219], v[70:73]
	v_mfma_f32_16x16x32_bf16 v[66:69], v[180:183], v[216:219], v[66:69]
	s_barrier
	s_add_i32 s43, s43, s30
	v_lshl_add_u64 v[220:221], s[24:25], 0, v[0:1]
	s_mov_b32 m0, s43
	ds_read_b128 v[184:187], v199 offset:16384
	ds_read_b128 v[188:191], v199 offset:17408
	ds_read_b128 v[192:195], v199 offset:18432
	ds_read_b128 v[200:203], v199 offset:19456
	ds_read_b128 v[204:207], v199 offset:20480
	ds_read_b128 v[208:211], v199 offset:21504
	ds_read_b128 v[212:215], v199 offset:22528
	ds_read_b128 v[216:219], v199 offset:23552
	global_load_lds_dwordx4 v[220:221], off
	s_add_i32 m0, s43, 0x2000
	s_add_u32 vcc_lo, s24, 0x80000
	v_lshl_add_u64 v[222:223], s[24:25], 0, v[126:127]
	s_addc_u32 vcc_hi, s25, 0
	s_add_i32 s43, s48, s30
	global_load_lds_dwordx4 v[222:223], off
	v_lshl_add_u64 v[224:225], vcc, 0, v[0:1]
	s_mov_b32 m0, s43
	v_lshl_add_u64 v[226:227], s[26:27], 0, v[126:127]
	global_load_lds_dwordx4 v[224:225], off
	s_add_i32 m0, s43, 0x2000
	v_lshl_add_u64 v[224:225], vcc, 0, v[126:127]
	global_load_lds_dwordx4 v[224:225], off
	s_mov_b32 m0, s31
	v_lshl_add_u64 v[224:225], s[26:27], 0, v[0:1]
	global_load_lds_dwordx4 v[224:225], off
	s_mov_b32 m0, s34
	s_nop 0
	global_load_lds_dwordx4 v[226:227], off
	s_waitcnt vmcnt(8) lgkmcnt(0)
	s_barrier
; #define PG8_STAGE(bufoff, gbase, voff) do { _Pragma("unroll") for (int _i = 0; _i < 2; ++_i) \
;         __builtin_amdgcn_global_load_lds((const unsigned*)((const char*)(gbase) + (voff)[_i]), (PG8_LAS unsigned*)(lds + (bufoff) + ldsw + _i * 8192), 16, 0, 0); } while (0)
; #define PG8_LDA(dst, b, h) do { _Pragma("unroll") for (int m = 0; m < 4; ++m) _Pragma("unroll") for (int k = 0; k < 2; ++k) dst[m][k] = *(const PG8_LAS bf16x8*)(lds + PG8_SA(b, h) + aoff + m * 2048 + k * 1024); } while (0)
; #define PG8_LDB(dst, b, h) do { _Pragma("unroll") for (int n = 0; n < 2; ++n) _Pragma("unroll") for (int k = 0; k < 2; ++k) dst[n][k] = *(const PG8_LAS bf16x8*)(lds + PG8_SB(b, h) + boff + n * 2048 + k * 1024); } while (0)
; #define PG8_MMA(ai, bj, At, Bt) do { __builtin_amdgcn_s_setprio(1); _Pragma("unroll") for (int m = 0; m < 4; ++m) _Pragma("unroll") for (int n = 0; n < 2; ++n) _Pragma("unroll") for (int k = 0; k < 2; ++k) \
;         acc[ai][bj][m][n] = __builtin_amdgcn_mfma_f32_16x16x32_bf16(Bt[n][k], At[m][k], acc[ai][bj][m][n], 0, 0, 0); __builtin_amdgcn_s_setprio(0); } while (0)
; #define PG8_WAIT_V(n) asm volatile("s_waitcnt vmcnt(" #n ")" ::: "memory")
; #define PG8_WAIT_L(n) asm volatile("s_waitcnt lgkmcnt(" #n ")" ::: "memory")
; #define PG8_BAR __builtin_amdgcn_s_barrier()
; #define PG8_SCHED __builtin_amdgcn_sched_barrier(0)
; template <class Epi, class Sched, bool ALIGN_EPI = false, bool SP2 = false>
; __device__ __forceinline__ void gemm_phase(PG8_LAS unsigned char* lds, const Gemm g, const Sched& S, const Epi& E) {
;     ...
;             PG8_WAIT_V(8); PG8_WAIT_L(0); PG8_BAR; PG8_MMA(1, 0, At, B0); PG8_MMA(1, 1, At, B1); PG8_BAR; PG8_SCHED;
;             PG8_LDB(B0, 1, 0); PG8_LDB(B1, 1, 1); PG8_SCHED; PG8_LDA(At, 1, 0); PG8_STAGE(PG8_SA(0, 1), a2 + hstep, voffA);
;             PG8_WAIT_V(8); PG8_WAIT_L(0); PG8_BAR; PG8_MMA(0, 0, At, B0); PG8_MMA(0, 1, At, B1); PG8_BAR; PG8_SCHED;
	v_mfma_f32_16x16x32_bf16 v[62:65], v[152:155], v[184:187], v[62:65]
	v_mfma_f32_16x16x32_bf16 v[58:61], v[160:163], v[184:187], v[58:61]
	v_mfma_f32_16x16x32_bf16 v[46:49], v[152:155], v[192:195], v[46:49]
	v_mfma_f32_16x16x32_bf16 v[42:45], v[160:163], v[192:195], v[42:45]
	v_mfma_f32_16x16x32_bf16 v[30:33], v[152:155], v[204:207], v[30:33]
	v_mfma_f32_16x16x32_bf16 v[26:29], v[160:163], v[204:207], v[26:29]
	v_mfma_f32_16x16x32_bf16 v[14:17], v[152:155], v[212:215], v[14:17]
	v_mfma_f32_16x16x32_bf16 v[10:13], v[160:163], v[212:215], v[10:13]
	v_mfma_f32_16x16x32_bf16 v[62:65], v[156:159], v[188:191], v[62:65]
	v_mfma_f32_16x16x32_bf16 v[58:61], v[164:167], v[188:191], v[58:61]
	v_mfma_f32_16x16x32_bf16 v[46:49], v[156:159], v[200:203], v[46:49]
	v_mfma_f32_16x16x32_bf16 v[42:45], v[164:167], v[200:203], v[42:45]
	v_mfma_f32_16x16x32_bf16 v[30:33], v[156:159], v[208:211], v[30:33]
	v_mfma_f32_16x16x32_bf16 v[26:29], v[164:167], v[208:211], v[26:29]
	v_mfma_f32_16x16x32_bf16 v[14:17], v[156:159], v[216:219], v[14:17]
	v_mfma_f32_16x16x32_bf16 v[10:13], v[164:167], v[216:219], v[10:13]
	v_mfma_f32_16x16x32_bf16 v[54:57], v[168:171], v[184:187], v[54:57]
	v_mfma_f32_16x16x32_bf16 v[50:53], v[176:179], v[184:187], v[50:53]
	v_mfma_f32_16x16x32_bf16 v[38:41], v[168:171], v[192:195], v[38:41]
	v_mfma_f32_16x16x32_bf16 v[34:37], v[176:179], v[192:195], v[34:37]
	v_mfma_f32_16x16x32_bf16 v[22:25], v[168:171], v[204:207], v[22:25]
	v_mfma_f32_16x16x32_bf16 v[18:21], v[176:179], v[204:207], v[18:21]
	v_mfma_f32_16x16x32_bf16 v[6:9], v[168:171], v[212:215], v[6:9]
	v_mfma_f32_16x16x32_bf16 v[2:5], v[176:179], v[212:215], v[2:5]
	v_mfma_f32_16x16x32_bf16 v[54:57], v[172:175], v[188:191], v[54:57]
	v_mfma_f32_16x16x32_bf16 v[50:53], v[180:183], v[188:191], v[50:53]
	v_mfma_f32_16x16x32_bf16 v[38:41], v[172:175], v[200:203], v[38:41]
	v_mfma_f32_16x16x32_bf16 v[34:37], v[180:183], v[200:203], v[34:37]
	v_mfma_f32_16x16x32_bf16 v[22:25], v[172:175], v[208:211], v[22:25]
	v_mfma_f32_16x16x32_bf16 v[18:21], v[180:183], v[208:211], v[18:21]
	v_mfma_f32_16x16x32_bf16 v[6:9], v[172:175], v[216:219], v[6:9]
	v_mfma_f32_16x16x32_bf16 v[2:5], v[180:183], v[216:219], v[2:5]
	s_barrier
	s_add_i32 s43, 0, 0x18000
	s_add_i32 s48, 0, 0x1c000
	v_add_u32_e32 v164, s43, v197
	v_add_u32_e32 v180, s48, v197
	ds_read_b128 v[152:155], v164
	ds_read_b128 v[156:159], v164 offset:1024
	ds_read_b128 v[160:163], v164 offset:2048
	ds_read_b128 v[164:167], v164 offset:3072
	ds_read_b128 v[168:171], v180
	ds_read_b128 v[172:175], v180 offset:1024
	ds_read_b128 v[176:179], v180 offset:2048
	ds_read_b128 v[180:183], v180 offset:3072
	s_add_u32 s26, s26, 0x80000
	s_addc_u32 s27, s27, 0
	s_mov_b32 m0, s35
	ds_read_b128 v[184:187], v199 offset:32768
	ds_read_b128 v[188:191], v199 offset:33792
	ds_read_b128 v[192:195], v199 offset:34816
	ds_read_b128 v[200:203], v199 offset:35840
	ds_read_b128 v[204:207], v199 offset:36864
	ds_read_b128 v[208:211], v199 offset:37888
	ds_read_b128 v[212:215], v199 offset:38912
	ds_read_b128 v[216:219], v199 offset:39936
	global_load_lds_dwordx4 v0, s[26:27]
	s_mov_b32 m0, s76
	s_nop 0
	global_load_lds_dwordx4 v126, s[26:27]
	s_waitcnt vmcnt(8) lgkmcnt(0)
	s_barrier
	v_mfma_f32_16x16x32_bf16 v[144:147], v[152:155], v[184:187], v[144:147]
	v_mfma_f32_16x16x32_bf16 v[122:125], v[160:163], v[184:187], v[122:125]
	v_mfma_f32_16x16x32_bf16 v[110:113], v[152:155], v[192:195], v[110:113]
	v_mfma_f32_16x16x32_bf16 v[106:109], v[160:163], v[192:195], v[106:109]
	v_mfma_f32_16x16x32_bf16 v[94:97], v[152:155], v[204:207], v[94:97]
	v_mfma_f32_16x16x32_bf16 v[90:93], v[160:163], v[204:207], v[90:93]
	v_mfma_f32_16x16x32_bf16 v[78:81], v[152:155], v[212:215], v[78:81]
	v_mfma_f32_16x16x32_bf16 v[74:77], v[160:163], v[212:215], v[74:77]
	v_mfma_f32_16x16x32_bf16 v[144:147], v[156:159], v[188:191], v[144:147]
	v_mfma_f32_16x16x32_bf16 v[122:125], v[164:167], v[188:191], v[122:125]
	v_mfma_f32_16x16x32_bf16 v[110:113], v[156:159], v[200:203], v[110:113]
	v_mfma_f32_16x16x32_bf16 v[106:109], v[164:167], v[200:203], v[106:109]
	v_mfma_f32_16x16x32_bf16 v[94:97], v[156:159], v[208:211], v[94:97]
	v_mfma_f32_16x16x32_bf16 v[90:93], v[164:167], v[208:211], v[90:93]
	v_mfma_f32_16x16x32_bf16 v[78:81], v[156:159], v[216:219], v[78:81]
	v_mfma_f32_16x16x32_bf16 v[74:77], v[164:167], v[216:219], v[74:77]
	v_mfma_f32_16x16x32_bf16 v[118:121], v[168:171], v[184:187], v[118:121]
	v_mfma_f32_16x16x32_bf16 v[114:117], v[176:179], v[184:187], v[114:117]
	v_mfma_f32_16x16x32_bf16 v[102:105], v[168:171], v[192:195], v[102:105]
	v_mfma_f32_16x16x32_bf16 v[98:101], v[176:179], v[192:195], v[98:101]
	v_mfma_f32_16x16x32_bf16 v[86:89], v[168:171], v[204:207], v[86:89]
	v_mfma_f32_16x16x32_bf16 v[82:85], v[176:179], v[204:207], v[82:85]
	v_mfma_f32_16x16x32_bf16 v[70:73], v[168:171], v[212:215], v[70:73]
	v_mfma_f32_16x16x32_bf16 v[66:69], v[176:179], v[212:215], v[66:69]
	v_mfma_f32_16x16x32_bf16 v[118:121], v[172:175], v[188:191], v[118:121]
	v_mfma_f32_16x16x32_bf16 v[114:117], v[180:183], v[188:191], v[114:117]
	v_mfma_f32_16x16x32_bf16 v[102:105], v[172:175], v[200:203], v[102:105]
	v_mfma_f32_16x16x32_bf16 v[98:101], v[180:183], v[200:203], v[98:101]
	v_mfma_f32_16x16x32_bf16 v[86:89], v[172:175], v[208:211], v[86:89]
	v_mfma_f32_16x16x32_bf16 v[82:85], v[180:183], v[208:211], v[82:85]
	v_mfma_f32_16x16x32_bf16 v[70:73], v[172:175], v[216:219], v[70:73]
	v_mfma_f32_16x16x32_bf16 v[66:69], v[180:183], v[216:219], v[66:69]
	s_barrier
; #define PG8_STAGE(bufoff, gbase, voff) do { _Pragma("unroll") for (int _i = 0; _i < 2; ++_i) \
;         __builtin_amdgcn_global_load_lds((const unsigned*)((const char*)(gbase) + (voff)[_i]), (PG8_LAS unsigned*)(lds + (bufoff) + ldsw + _i * 8192), 16, 0, 0); } while (0)
; #define PG8_LDA(dst, b, h) do { _Pragma("unroll") for (int m = 0; m < 4; ++m) _Pragma("unroll") for (int k = 0; k < 2; ++k) dst[m][k] = *(const PG8_LAS bf16x8*)(lds + PG8_SA(b, h) + aoff + m * 2048 + k * 1024); } while (0)
; #define PG8_MMA(ai, bj, At, Bt) do { __builtin_amdgcn_s_setprio(1); _Pragma("unroll") for (int m = 0; m < 4; ++m) _Pragma("unroll") for (int n = 0; n < 2; ++n) _Pragma("unroll") for (int k = 0; k < 2; ++k) \
;         acc[ai][bj][m][n] = __builtin_amdgcn_mfma_f32_16x16x32_bf16(Bt[n][k], At[m][k], acc[ai][bj][m][n], 0, 0, 0); __builtin_amdgcn_s_setprio(0); } while (0)
; #define PG8_WAIT_V(n) asm volatile("s_waitcnt vmcnt(" #n ")" ::: "memory")
; #define PG8_WAIT_L(n) asm volatile("s_waitcnt lgkmcnt(" #n ")" ::: "memory")
; #define PG8_BAR __builtin_amdgcn_s_barrier()
; #define PG8_SCHED __builtin_amdgcn_sched_barrier(0)
; template <class Epi, class Sched, bool ALIGN_EPI = false, bool SP2 = false>
; __device__ __forceinline__ void gemm_phase(PG8_LAS unsigned char* lds, const Gemm g, const Sched& S, const Epi& E) {
;     ...
;         for (int t = 0; t < nt; t += 2) {
;             if constexpr (Epi::HAS_MID) { if (t == Epi::MID0 || t == Epi::MID1) E.mid(acc, cur, wr, wc, fr, fq, t == Epi::MID0 ? 0 : 1); }
;             const bool last = (t == nt - 2);
;             const char* a1 = cA + (size_t)(t + 1) * kstep;
;             const char* a2 = last ? nA : cA + (size_t)(t + 2) * kstep; const char* b2 = last ? nB : cB + (size_t)(t + 2) * kstep;
;     ...
;             PG8_LDA(At, 1, 1); PG8_STAGE(PG8_SB(1, 0), b3, voffB); PG8_STAGE(PG8_SB(1, 1), b3 + hstep, voffB); PG8_STAGE(PG8_SA(1, 0), a3, voffA);
;             PG8_WAIT_V(8); PG8_WAIT_L(0); PG8_BAR; PG8_MMA(1, 0, At, B0); PG8_MMA(1, 1, At, B1); PG8_BAR; PG8_SCHED;
	s_add_i32 s26, s43, s30
	v_lshl_add_u64 v[220:221], v[220:221], 0, s[64:65]
	s_mov_b32 m0, s26
	ds_read_b128 v[184:187], v199 offset:49152
	ds_read_b128 v[188:191], v199 offset:50176
	ds_read_b128 v[192:195], v199 offset:51200
	ds_read_b128 v[200:203], v199 offset:52224
	ds_read_b128 v[204:207], v199 offset:53248
	ds_read_b128 v[208:211], v199 offset:54272
	ds_read_b128 v[212:215], v199 offset:55296
	ds_read_b128 v[216:219], v199 offset:56320
	global_load_lds_dwordx4 v[220:221], off
	s_add_i32 m0, s26, 0x2000
	s_add_u32 s24, s24, 0x80080
	v_lshl_add_u64 v[220:221], v[222:223], 0, s[64:65]
	s_addc_u32 s25, s25, 0
	s_add_i32 s26, s48, s30
	global_load_lds_dwordx4 v[220:221], off
	s_mov_b32 m0, s26
	s_nop 0
	global_load_lds_dwordx4 v0, s[24:25]
	s_add_i32 m0, s26, 0x2000
	s_nop 0
	global_load_lds_dwordx4 v126, s[24:25]
	s_mov_b32 m0, s82
	v_lshl_add_u64 v[220:221], v[224:225], 0, s[64:65]
	global_load_lds_dwordx4 v[220:221], off
	s_mov_b32 m0, s83
	v_lshl_add_u64 v[220:221], v[226:227], 0, s[64:65]
	global_load_lds_dwordx4 v[220:221], off
	s_waitcnt vmcnt(8) lgkmcnt(0)
	s_barrier
	v_mfma_f32_16x16x32_bf16 v[62:65], v[152:155], v[184:187], v[62:65]
	v_mfma_f32_16x16x32_bf16 v[58:61], v[160:163], v[184:187], v[58:61]
	v_mfma_f32_16x16x32_bf16 v[46:49], v[152:155], v[192:195], v[46:49]
	v_mfma_f32_16x16x32_bf16 v[42:45], v[160:163], v[192:195], v[42:45]
	v_mfma_f32_16x16x32_bf16 v[30:33], v[152:155], v[204:207], v[30:33]
	v_mfma_f32_16x16x32_bf16 v[26:29], v[160:163], v[204:207], v[26:29]
	v_mfma_f32_16x16x32_bf16 v[14:17], v[152:155], v[212:215], v[14:17]
	v_mfma_f32_16x16x32_bf16 v[10:13], v[160:163], v[212:215], v[10:13]
	v_mfma_f32_16x16x32_bf16 v[62:65], v[156:159], v[188:191], v[62:65]
	v_mfma_f32_16x16x32_bf16 v[58:61], v[164:167], v[188:191], v[58:61]
	v_mfma_f32_16x16x32_bf16 v[46:49], v[156:159], v[200:203], v[46:49]
	v_mfma_f32_16x16x32_bf16 v[42:45], v[164:167], v[200:203], v[42:45]
	v_mfma_f32_16x16x32_bf16 v[30:33], v[156:159], v[208:211], v[30:33]
	v_mfma_f32_16x16x32_bf16 v[26:29], v[164:167], v[208:211], v[26:29]
	v_mfma_f32_16x16x32_bf16 v[14:17], v[156:159], v[216:219], v[14:17]
	v_mfma_f32_16x16x32_bf16 v[10:13], v[164:167], v[216:219], v[10:13]
	v_mfma_f32_16x16x32_bf16 v[54:57], v[168:171], v[184:187], v[54:57]
	v_mfma_f32_16x16x32_bf16 v[50:53], v[176:179], v[184:187], v[50:53]
	v_mfma_f32_16x16x32_bf16 v[38:41], v[168:171], v[192:195], v[38:41]
	v_mfma_f32_16x16x32_bf16 v[34:37], v[176:179], v[192:195], v[34:37]
	v_mfma_f32_16x16x32_bf16 v[22:25], v[168:171], v[204:207], v[22:25]
	v_mfma_f32_16x16x32_bf16 v[18:21], v[176:179], v[204:207], v[18:21]
	v_mfma_f32_16x16x32_bf16 v[6:9], v[168:171], v[212:215], v[6:9]
	v_mfma_f32_16x16x32_bf16 v[2:5], v[176:179], v[212:215], v[2:5]
	v_mfma_f32_16x16x32_bf16 v[54:57], v[172:175], v[188:191], v[54:57]
	v_mfma_f32_16x16x32_bf16 v[50:53], v[180:183], v[188:191], v[50:53]
	v_mfma_f32_16x16x32_bf16 v[38:41], v[172:175], v[200:203], v[38:41]
	v_mfma_f32_16x16x32_bf16 v[34:37], v[180:183], v[200:203], v[34:37]
	v_mfma_f32_16x16x32_bf16 v[22:25], v[172:175], v[208:211], v[22:25]
	v_mfma_f32_16x16x32_bf16 v[18:21], v[180:183], v[208:211], v[18:21]
	v_mfma_f32_16x16x32_bf16 v[6:9], v[172:175], v[216:219], v[6:9]
	v_mfma_f32_16x16x32_bf16 v[2:5], v[180:183], v[216:219], v[2:5]
	s_barrier
	s_add_i32 s42, s42, 2
	s_add_u32 s0, s0, 0x100
	s_addc_u32 s1, s1, 0
	s_add_u32 s40, s40, 0x100
	s_addc_u32 s41, s41, 0
	s_cmp_gt_u32 s42, 29
	s_cbranch_scc0 .LBB0_963
	s_and_b64 vcc, exec, s[14:15]
	s_cbranch_vccz .LBB0_966
	s_barrier
